# prologue weight transposes: each item's two 16-load trips unrolled so all 32 global loads are in flight before the first wait (second register set v80+)
# baseline (speedup 1.0000x reference)
; #define LDS_WAIT() asm volatile("s_waitcnt lgkmcnt(0)" ::: "memory")
;     const int nblk = N / 32, kb = item / nblk, nb = item % nblk, k0 = 64 * kb, n0 = 32 * nb;
;     const bool pg = (pmode == 1 && n0 < 4096) || (pmode == 2 && (n0 % 192) >= 128);
; #pragma unroll 8
;     for (int i = 0; i < 32; ++i) { const int kk = 2 * i + (lane >> 5); scr[kk * 33 + (lane & 31)] = W[(size_t)(k0 + kk) * N + n0 + (lane & 31)]; }
;     LDS_WAIT(); asm volatile("" ::: "memory");
.LBB0_405:
	v_mov_b32_e32 v81, v1
	s_lshl_b32 s17, s12, 1
	s_lshl_b32 s18, s13, 1
	v_or_b32_e32 v80, s18, v24
	s_add_i32 s20, s17, 4
	s_add_i32 s21, s18, 4
	v_mov_b32_e32 v117, v1
	s_add_i32 s23, s18, 8
	v_lshlrev_b64 v[130:131], 14, v[80:81]
	v_or_b32_e32 v116, s20, v5
	v_or_b32_e32 v80, s21, v24
	v_mov_b32_e32 v115, v1
	v_or_b32_e32 v114, s17, v5
	s_add_i32 s25, s18, 12
	v_lshlrev_b64 v[116:117], 14, v[116:117]
	v_lshlrev_b64 v[132:133], 14, v[80:81]
	v_or_b32_e32 v80, s23, v24
	s_add_i32 s22, s17, 8
	s_add_i32 s24, s17, 12
	s_add_i32 s27, s18, 16
	v_lshlrev_b64 v[114:115], 14, v[114:115]
	v_lshl_add_u64 v[130:131], v[22:23], 0, v[130:131]
	v_lshl_add_u64 v[116:117], v[22:23], 0, v[116:117]
	v_lshlrev_b64 v[134:135], 14, v[80:81]
	v_or_b32_e32 v80, s25, v24
	v_mov_b32_e32 v119, v1
	v_mov_b32_e32 v121, v1
	s_add_i32 s29, s18, 20
	v_or_b32_e32 v118, s22, v5
	v_or_b32_e32 v120, s24, v5
	v_lshl_add_u64 v[114:115], v[22:23], 0, v[114:115]
	v_lshl_add_u64 v[132:133], v[22:23], 0, v[132:133]
	global_load_dword v101, v[130:131], off
	global_load_dword v113, v[114:115], off
	global_load_dword v146, v[132:133], off
	global_load_dword v147, v[116:117], off
	v_lshlrev_b64 v[116:117], 14, v[80:81]
	v_or_b32_e32 v80, s27, v24
	s_add_i32 s26, s17, 16
	s_add_i32 s28, s17, 20
	s_add_i32 s31, s18, 24
	v_lshlrev_b64 v[118:119], 14, v[118:119]
	v_lshlrev_b64 v[120:121], 14, v[120:121]
	v_lshl_add_u64 v[114:115], v[22:23], 0, v[134:135]
	v_lshl_add_u64 v[116:117], v[22:23], 0, v[116:117]
	v_lshlrev_b64 v[130:131], 14, v[80:81]
	v_or_b32_e32 v80, s29, v24
	v_mov_b32_e32 v123, v1
	v_mov_b32_e32 v125, v1
	s_add_i32 s30, s17, 24
	s_add_i32 s33, s17, 28
	s_add_i32 s35, s18, 28
	v_or_b32_e32 v122, s26, v5
	v_or_b32_e32 v124, s28, v5
	v_lshl_add_u64 v[118:119], v[22:23], 0, v[118:119]
	v_lshl_add_u64 v[120:121], v[22:23], 0, v[120:121]
	global_load_dword v148, v[114:115], off
	global_load_dword v149, v[118:119], off
	global_load_dword v150, v[116:117], off
	global_load_dword v151, v[120:121], off
	v_lshlrev_b64 v[116:117], 14, v[80:81]
	v_or_b32_e32 v80, s31, v24
	v_mov_b32_e32 v127, v1
	v_mov_b32_e32 v129, v1
	v_or_b32_e32 v126, s30, v5
	v_or_b32_e32 v128, s33, v5
	v_lshlrev_b64 v[122:123], 14, v[122:123]
	v_lshlrev_b64 v[124:125], 14, v[124:125]
	v_lshl_add_u64 v[114:115], v[22:23], 0, v[130:131]
	v_lshl_add_u64 v[116:117], v[22:23], 0, v[116:117]
	v_lshlrev_b64 v[118:119], 14, v[80:81]
	v_or_b32_e32 v80, s35, v24
	v_lshlrev_b64 v[126:127], 14, v[126:127]
	v_lshlrev_b64 v[128:129], 14, v[128:129]
	v_lshl_add_u64 v[122:123], v[22:23], 0, v[122:123]
	v_lshl_add_u64 v[124:125], v[22:23], 0, v[124:125]
	global_load_dword v152, v[114:115], off
	global_load_dword v153, v[122:123], off
	global_load_dword v154, v[116:117], off
	global_load_dword v155, v[124:125], off
	v_lshl_add_u64 v[114:115], v[22:23], 0, v[118:119]
	v_lshlrev_b64 v[116:117], 14, v[80:81]
	v_lshl_add_u64 v[126:127], v[22:23], 0, v[126:127]
	v_lshl_add_u64 v[128:129], v[22:23], 0, v[128:129]
	v_lshl_add_u64 v[116:117], v[22:23], 0, v[116:117]
	global_load_dword v80, v[114:115], off
	global_load_dword v156, v[126:127], off
	global_load_dword v157, v[116:117], off
	global_load_dword v158, v[128:129], off
	v_or_b32_e32 v116, s17, v3
	v_or_b32_e32 v114, s18, v2
	s_add_i32 s13, s13, 16
	s_add_i32 s12, s12, 16
	s_add_i32 s16, s16, -16
	v_mad_u64_u32 v[114:115], s[18:19], v114, s1, v[6:7]
	v_mad_u64_u32 v[116:117], s[18:19], v116, s1, v[6:7]
	v_or_b32_e32 v115, s20, v3
	v_or_b32_e32 v117, s21, v2
	v_or_b32_e32 v124, s22, v3
	v_or_b32_e32 v122, s23, v2
	v_or_b32_e32 v128, s24, v3
	v_or_b32_e32 v126, s25, v2
	v_or_b32_e32 v132, s26, v3
	v_or_b32_e32 v130, s27, v2
	v_or_b32_e32 v136, s28, v3
	v_or_b32_e32 v134, s29, v2
	v_or_b32_e32 v140, s30, v3
	v_or_b32_e32 v138, s31, v2
	v_or_b32_e32 v144, s33, v3
	v_or_b32_e32 v142, s35, v2
	s_cmp_lg_u32 s16, 0
	v_mad_u64_u32 v[118:119], s[18:19], v117, s1, v[6:7]
	v_mad_u64_u32 v[120:121], s[18:19], v115, s1, v[6:7]
	v_mad_u64_u32 v[122:123], s[18:19], v122, s1, v[6:7]
	v_mad_u64_u32 v[124:125], s[18:19], v124, s1, v[6:7]
	v_mad_u64_u32 v[126:127], s[18:19], v126, s1, v[6:7]
	v_mad_u64_u32 v[128:129], s[18:19], v128, s1, v[6:7]
	v_mad_u64_u32 v[130:131], s[18:19], v130, s1, v[6:7]
	v_mad_u64_u32 v[132:133], s[18:19], v132, s1, v[6:7]
	v_mad_u64_u32 v[134:135], s[18:19], v134, s1, v[6:7]
	v_mad_u64_u32 v[136:137], s[18:19], v136, s1, v[6:7]
	v_mad_u64_u32 v[138:139], s[18:19], v138, s1, v[6:7]
	v_mad_u64_u32 v[140:141], s[18:19], v140, s1, v[6:7]
	v_mad_u64_u32 v[142:143], s[18:19], v142, s1, v[6:7]
	v_mad_u64_u32 v[144:145], s[18:19], v144, s1, v[6:7]
	s_lshl_b32 s17, s12, 1
	s_lshl_b32 s18, s13, 1
	v_or_b32_e32 v0, s18, v24
	s_add_i32 s20, s17, 4
	s_add_i32 s21, s18, 4
	v_mov_b32_e32 v37, v1
	s_add_i32 s23, s18, 8
	v_lshlrev_b64 v[50:51], 14, v[0:1]
	v_or_b32_e32 v36, s20, v5
	v_or_b32_e32 v0, s21, v24
	v_mov_b32_e32 v35, v1
	v_or_b32_e32 v34, s17, v5
	s_add_i32 s25, s18, 12
	v_lshlrev_b64 v[36:37], 14, v[36:37]
	v_lshlrev_b64 v[52:53], 14, v[0:1]
	v_or_b32_e32 v0, s23, v24
	s_add_i32 s22, s17, 8
	s_add_i32 s24, s17, 12
	s_add_i32 s27, s18, 16
	v_lshlrev_b64 v[34:35], 14, v[34:35]
	v_lshl_add_u64 v[50:51], v[22:23], 0, v[50:51]
	v_lshl_add_u64 v[36:37], v[22:23], 0, v[36:37]
	v_lshlrev_b64 v[54:55], 14, v[0:1]
	v_or_b32_e32 v0, s25, v24
	v_mov_b32_e32 v39, v1
	v_mov_b32_e32 v41, v1
	s_add_i32 s29, s18, 20
	v_or_b32_e32 v38, s22, v5
	v_or_b32_e32 v40, s24, v5
	v_lshl_add_u64 v[34:35], v[22:23], 0, v[34:35]
	v_lshl_add_u64 v[52:53], v[22:23], 0, v[52:53]
	global_load_dword v21, v[50:51], off
	global_load_dword v33, v[34:35], off
	global_load_dword v66, v[52:53], off
;     ...
; #pragma unroll 8
;     for (int i = 0; i < 32; ++i) { const int kk = 2 * i + (lane >> 5); scr[kk * 33 + (lane & 31)] = W[(size_t)(k0 + kk) * N + n0 + (lane & 31)]; }
	global_load_dword v67, v[36:37], off
	v_lshlrev_b64 v[36:37], 14, v[0:1]
	v_or_b32_e32 v0, s27, v24
	s_add_i32 s26, s17, 16
	s_add_i32 s28, s17, 20
	s_add_i32 s31, s18, 24
	v_lshlrev_b64 v[38:39], 14, v[38:39]
	v_lshlrev_b64 v[40:41], 14, v[40:41]
	v_lshl_add_u64 v[34:35], v[22:23], 0, v[54:55]
	v_lshl_add_u64 v[36:37], v[22:23], 0, v[36:37]
	v_lshlrev_b64 v[50:51], 14, v[0:1]
	v_or_b32_e32 v0, s29, v24
	v_mov_b32_e32 v43, v1
	v_mov_b32_e32 v45, v1
	s_add_i32 s30, s17, 24
	s_add_i32 s33, s17, 28
	s_add_i32 s35, s18, 28
	v_or_b32_e32 v42, s26, v5
	v_or_b32_e32 v44, s28, v5
	v_lshl_add_u64 v[38:39], v[22:23], 0, v[38:39]
	v_lshl_add_u64 v[40:41], v[22:23], 0, v[40:41]
	global_load_dword v68, v[34:35], off
	global_load_dword v69, v[38:39], off
	global_load_dword v70, v[36:37], off
	global_load_dword v71, v[40:41], off
	v_lshlrev_b64 v[36:37], 14, v[0:1]
	v_or_b32_e32 v0, s31, v24
	v_mov_b32_e32 v47, v1
	v_mov_b32_e32 v49, v1
	v_or_b32_e32 v46, s30, v5
	v_or_b32_e32 v48, s33, v5
	v_lshlrev_b64 v[42:43], 14, v[42:43]
	v_lshlrev_b64 v[44:45], 14, v[44:45]
	v_lshl_add_u64 v[34:35], v[22:23], 0, v[50:51]
	v_lshl_add_u64 v[36:37], v[22:23], 0, v[36:37]
	v_lshlrev_b64 v[38:39], 14, v[0:1]
	v_or_b32_e32 v0, s35, v24
	v_lshlrev_b64 v[46:47], 14, v[46:47]
	v_lshlrev_b64 v[48:49], 14, v[48:49]
	v_lshl_add_u64 v[42:43], v[22:23], 0, v[42:43]
	v_lshl_add_u64 v[44:45], v[22:23], 0, v[44:45]
	global_load_dword v72, v[34:35], off
	global_load_dword v73, v[42:43], off
	global_load_dword v74, v[36:37], off
	global_load_dword v75, v[44:45], off
	v_lshl_add_u64 v[34:35], v[22:23], 0, v[38:39]
	v_lshlrev_b64 v[36:37], 14, v[0:1]
	v_lshl_add_u64 v[46:47], v[22:23], 0, v[46:47]
	v_lshl_add_u64 v[48:49], v[22:23], 0, v[48:49]
	v_lshl_add_u64 v[36:37], v[22:23], 0, v[36:37]
	global_load_dword v0, v[34:35], off
	global_load_dword v76, v[46:47], off
	global_load_dword v77, v[36:37], off
	global_load_dword v78, v[48:49], off
	v_or_b32_e32 v36, s17, v3
	v_or_b32_e32 v34, s18, v2
	s_add_i32 s13, s13, 16
	s_add_i32 s12, s12, 16
	s_add_i32 s16, s16, -16
	v_mad_u64_u32 v[34:35], s[18:19], v34, s1, v[6:7]
	v_mad_u64_u32 v[36:37], s[18:19], v36, s1, v[6:7]
	v_or_b32_e32 v35, s20, v3
	v_or_b32_e32 v37, s21, v2
	v_or_b32_e32 v44, s22, v3
	v_or_b32_e32 v42, s23, v2
	v_or_b32_e32 v48, s24, v3
	v_or_b32_e32 v46, s25, v2
	v_or_b32_e32 v52, s26, v3
	v_or_b32_e32 v50, s27, v2
	v_or_b32_e32 v56, s28, v3
	v_or_b32_e32 v54, s29, v2
	v_or_b32_e32 v60, s30, v3
	v_or_b32_e32 v58, s31, v2
	v_or_b32_e32 v64, s33, v3
	v_or_b32_e32 v62, s35, v2
	s_cmp_lg_u32 s16, 0
	v_mad_u64_u32 v[38:39], s[18:19], v37, s1, v[6:7]
	v_mad_u64_u32 v[40:41], s[18:19], v35, s1, v[6:7]
	v_mad_u64_u32 v[42:43], s[18:19], v42, s1, v[6:7]
	v_mad_u64_u32 v[44:45], s[18:19], v44, s1, v[6:7]
	v_mad_u64_u32 v[46:47], s[18:19], v46, s1, v[6:7]
	v_mad_u64_u32 v[48:49], s[18:19], v48, s1, v[6:7]
	v_mad_u64_u32 v[50:51], s[18:19], v50, s1, v[6:7]
	v_mad_u64_u32 v[52:53], s[18:19], v52, s1, v[6:7]
	v_mad_u64_u32 v[54:55], s[18:19], v54, s1, v[6:7]
	v_mad_u64_u32 v[56:57], s[18:19], v56, s1, v[6:7]
	v_mad_u64_u32 v[58:59], s[18:19], v58, s1, v[6:7]
	v_mad_u64_u32 v[60:61], s[18:19], v60, s1, v[6:7]
	v_mad_u64_u32 v[62:63], s[18:19], v62, s1, v[6:7]
	v_mad_u64_u32 v[64:65], s[18:19], v64, s1, v[6:7]
	s_waitcnt vmcnt(31)
	ds_write_b32 v114, v101
	s_waitcnt vmcnt(30)
	ds_write_b32 v116, v113
	s_waitcnt vmcnt(29)
	ds_write_b32 v118, v146
	s_waitcnt vmcnt(28)
	ds_write_b32 v120, v147
	s_waitcnt vmcnt(27)
	ds_write_b32 v122, v148
	s_waitcnt vmcnt(26)
	ds_write_b32 v124, v149
	s_waitcnt vmcnt(25)
	ds_write_b32 v126, v150
	s_waitcnt vmcnt(24)
	ds_write_b32 v128, v151
	s_waitcnt vmcnt(23)
	ds_write_b32 v130, v152
	s_waitcnt vmcnt(22)
	ds_write_b32 v132, v153
	s_waitcnt vmcnt(21)
	ds_write_b32 v134, v154
	s_waitcnt vmcnt(20)
	ds_write_b32 v136, v155
	s_waitcnt vmcnt(19)
	ds_write_b32 v138, v80
	s_waitcnt vmcnt(18)
	ds_write_b32 v140, v156
	s_waitcnt vmcnt(17)
	ds_write_b32 v142, v157
	s_waitcnt vmcnt(16)
	ds_write_b32 v144, v158
	s_waitcnt vmcnt(15)
	ds_write_b32 v34, v21
	s_waitcnt vmcnt(14)
	ds_write_b32 v36, v33
	s_waitcnt vmcnt(13)
	ds_write_b32 v38, v66
	s_waitcnt vmcnt(12)
	ds_write_b32 v40, v67
	s_waitcnt vmcnt(11)
	ds_write_b32 v42, v68
	s_waitcnt vmcnt(10)
	ds_write_b32 v44, v69
	s_waitcnt vmcnt(9)
	ds_write_b32 v46, v70
	s_waitcnt vmcnt(8)
	ds_write_b32 v48, v71
	s_waitcnt vmcnt(7)
	ds_write_b32 v50, v72
	s_waitcnt vmcnt(6)
	ds_write_b32 v52, v73
	s_waitcnt vmcnt(5)
	ds_write_b32 v54, v74
	s_waitcnt vmcnt(4)
	ds_write_b32 v56, v75
	s_waitcnt vmcnt(3)
	ds_write_b32 v58, v0
	s_waitcnt vmcnt(2)
	ds_write_b32 v60, v76
	s_waitcnt vmcnt(1)
	ds_write_b32 v62, v77
	s_waitcnt vmcnt(0)
; #define GAS __attribute__((address_space(1)))
; #define LAS __attribute__((address_space(3)))
; #define LDS_WAIT() asm volatile("s_waitcnt lgkmcnt(0)" ::: "memory")
; __device__ __forceinline__ unsigned pk2(float lo, float hi) { return f2bf(lo) | (f2bf(hi) << 16); }
;     ...
;     for (int i = 0; i < 32; ++i) { const int kk = 2 * i + (lane >> 5); scr[kk * 33 + (lane & 31)] = W[(size_t)(k0 + kk) * N + n0 + (lane & 31)]; }
;     LDS_WAIT(); asm volatile("" ::: "memory");
;     const int c = lane & 7;
; #pragma unroll
;     for (int j = 0; j < 4; ++j) { const int n = (lane >> 3) + 8 * j; const LAS float* s = scr + (8 * c) * 33 + n;
;         v4u o; o.x = pk2(s[0 * 33], s[1 * 33]); o.y = pk2(s[2 * 33], s[3 * 33]); o.z = pk2(s[4 * 33], s[5 * 33]); o.w = pk2(s[6 * 33], s[7 * 33]);
;         const int nr = pg ? (8 * ((n >> 2) & 3) + 4 * (n >> 4) + (n & 3)) : n;
;         *(GAS v4u*)(WT + (size_t)(n0 + nr) * K + k0 + 8 * c) = o; }
;     LDS_WAIT(); asm volatile("" ::: "memory");
	ds_write_b32 v64, v78
	s_waitcnt lgkmcnt(0)
	ds_read2_b32 v[22:23], v25 offset1:8
	ds_read2_b32 v[40:41], v25 offset0:33 offset1:41
	ds_read2_b32 v[42:43], v25 offset0:66 offset1:74
	ds_read2_b32 v[44:45], v25 offset0:99 offset1:107
	ds_read2_b32 v[46:47], v25 offset0:132 offset1:140
	ds_read2_b32 v[48:49], v25 offset0:165 offset1:173
	s_waitcnt lgkmcnt(5)
	v_bfe_u32 v0, v22, 16, 1
	v_add3_u32 v0, v22, v0, s85
	s_waitcnt lgkmcnt(4)
	v_bfe_u32 v5, v40, 16, 1
	v_lshrrev_b32_e32 v0, 16, v0
	v_add3_u32 v5, v40, v5, s85
	v_and_or_b32 v34, v5, s3, v0
	s_waitcnt lgkmcnt(3)
	v_bfe_u32 v0, v42, 16, 1
	v_add3_u32 v0, v42, v0, s85
	s_waitcnt lgkmcnt(2)
	v_bfe_u32 v5, v44, 16, 1
	ds_read2_b32 v[50:51], v25 offset0:198 offset1:206
	v_lshrrev_b32_e32 v0, 16, v0
	v_add3_u32 v5, v44, v5, s85
	ds_read2_b32 v[52:53], v25 offset0:231 offset1:239
	v_and_or_b32 v35, v5, s3, v0
	s_waitcnt lgkmcnt(3)
	v_bfe_u32 v0, v46, 16, 1
	v_add3_u32 v0, v46, v0, s85
	s_waitcnt lgkmcnt(2)
	v_bfe_u32 v5, v48, 16, 1
	v_lshrrev_b32_e32 v0, 16, v0
	v_add3_u32 v5, v48, v5, s85
	v_and_or_b32 v36, v5, s3, v0
	s_waitcnt lgkmcnt(1)
	v_bfe_u32 v0, v50, 16, 1
	v_add3_u32 v0, v50, v0, s85
	s_waitcnt lgkmcnt(0)
	v_bfe_u32 v5, v52, 16, 1
	v_lshrrev_b32_e32 v0, 16, v0
	v_add3_u32 v5, v52, v5, s85
	s_lshl_b32 s78, s11, 1
	v_and_or_b32 v37, v5, s3, v0
	v_or_b32_e32 v0, s10, v7
	v_lshl_add_u64 v[38:39], v[8:9], 0, s[78:79]
	v_lshlrev_b32_e32 v0, 10, v0
	v_lshl_add_u64 v[54:55], v[38:39], 0, v[0:1]
	v_bfe_u32 v0, v23, 16, 1
	v_add3_u32 v0, v23, v0, s85
	v_bfe_u32 v5, v41, 16, 1
	v_lshrrev_b32_e32 v0, 16, v0
	v_add3_u32 v5, v41, v5, s85
	global_store_dwordx4 v[54:55], v[34:37], off
	ds_read2_b32 v[22:23], v25 offset0:16 offset1:24
	s_nop 0
	v_and_or_b32 v34, v5, s3, v0
	v_bfe_u32 v0, v43, 16, 1
	v_add3_u32 v0, v43, v0, s85
	v_bfe_u32 v5, v45, 16, 1
	v_lshrrev_b32_e32 v0, 16, v0
	v_add3_u32 v5, v45, v5, s85
	v_and_or_b32 v35, v5, s3, v0
	v_bfe_u32 v0, v47, 16, 1
	v_add3_u32 v0, v47, v0, s85
	v_bfe_u32 v5, v49, 16, 1
	v_lshrrev_b32_e32 v0, 16, v0
	v_add3_u32 v5, v49, v5, s85
	v_and_or_b32 v36, v5, s3, v0
	v_bfe_u32 v0, v51, 16, 1
	v_add3_u32 v0, v51, v0, s85
	v_bfe_u32 v5, v53, 16, 1
	v_lshrrev_b32_e32 v0, 16, v0
	v_add3_u32 v5, v53, v5, s85
	v_and_or_b32 v37, v5, s3, v0
	v_or_b32_e32 v0, s10, v26
	v_lshlrev_b32_e32 v0, 10, v0
	v_lshl_add_u64 v[40:41], v[38:39], 0, v[0:1]
	global_store_dwordx4 v[40:41], v[34:37], off
	ds_read2_b32 v[40:41], v25 offset0:49 offset1:57
	ds_read2_b32 v[42:43], v25 offset0:82 offset1:90
	ds_read2_b32 v[44:45], v25 offset0:115 offset1:123
	s_waitcnt lgkmcnt(3)
	v_bfe_u32 v0, v22, 16, 1
	v_add3_u32 v0, v22, v0, s85
	s_waitcnt lgkmcnt(2)
	v_bfe_u32 v5, v40, 16, 1
	ds_read2_b32 v[46:47], v25 offset0:148 offset1:156
	v_lshrrev_b32_e32 v0, 16, v0
	v_add3_u32 v5, v40, v5, s85
	ds_read2_b32 v[48:49], v25 offset0:181 offset1:189
	v_and_or_b32 v34, v5, s3, v0
	s_waitcnt lgkmcnt(3)
	v_bfe_u32 v0, v42, 16, 1
	v_add3_u32 v0, v42, v0, s85
	s_waitcnt lgkmcnt(2)
	v_bfe_u32 v5, v44, 16, 1
	ds_read2_b32 v[50:51], v25 offset0:214 offset1:222
	v_lshrrev_b32_e32 v0, 16, v0
	v_add3_u32 v5, v44, v5, s85
	ds_read2_b32 v[52:53], v25 offset0:247 offset1:255
	v_and_or_b32 v35, v5, s3, v0
	s_waitcnt lgkmcnt(3)
	v_bfe_u32 v0, v46, 16, 1
	v_add3_u32 v0, v46, v0, s85
	s_waitcnt lgkmcnt(2)
	v_bfe_u32 v5, v48, 16, 1
	v_lshrrev_b32_e32 v0, 16, v0
	v_add3_u32 v5, v48, v5, s85
	v_and_or_b32 v36, v5, s3, v0
	s_waitcnt lgkmcnt(1)
	v_bfe_u32 v0, v50, 16, 1
	v_add3_u32 v0, v50, v0, s85
	s_waitcnt lgkmcnt(0)
	v_bfe_u32 v5, v52, 16, 1
	v_lshrrev_b32_e32 v0, 16, v0
	v_add3_u32 v5, v52, v5, s85
	v_and_or_b32 v37, v5, s3, v0
	v_or_b32_e32 v0, s10, v27
	v_lshlrev_b32_e32 v0, 10, v0
	v_lshl_add_u64 v[54:55], v[38:39], 0, v[0:1]
	v_bfe_u32 v0, v23, 16, 1
	v_add3_u32 v0, v23, v0, s85
	v_bfe_u32 v5, v41, 16, 1
	v_lshrrev_b32_e32 v0, 16, v0
	v_add3_u32 v5, v41, v5, s85
	global_store_dwordx4 v[54:55], v[34:37], off
	s_nop 1
	v_and_or_b32 v34, v5, s3, v0
	v_bfe_u32 v0, v43, 16, 1
	v_add3_u32 v0, v43, v0, s85
	v_bfe_u32 v5, v45, 16, 1
	v_lshrrev_b32_e32 v0, 16, v0
	v_add3_u32 v5, v45, v5, s85
	v_and_or_b32 v35, v5, s3, v0
	v_bfe_u32 v0, v47, 16, 1
	v_add3_u32 v0, v47, v0, s85
	v_bfe_u32 v5, v49, 16, 1
	v_lshrrev_b32_e32 v0, 16, v0
	v_add3_u32 v5, v49, v5, s85
	v_and_or_b32 v36, v5, s3, v0
	v_bfe_u32 v0, v51, 16, 1
	v_add3_u32 v0, v51, v0, s85
	v_bfe_u32 v5, v53, 16, 1
	v_lshrrev_b32_e32 v0, 16, v0
	v_add3_u32 v5, v53, v5, s85
	v_and_or_b32 v37, v5, s3, v0
	v_or_b32_e32 v0, s10, v28
	v_lshlrev_b32_e32 v0, 10, v0
	v_lshl_add_u64 v[22:23], v[38:39], 0, v[0:1]
	global_store_dwordx4 v[22:23], v[34:37], off
	s_waitcnt lgkmcnt(0)
	s_mov_b64 s[10:11], 0

;     ...
; #pragma unroll 8
;     for (int i = 0; i < 32; ++i) { const int kk = 2 * i + (lane >> 5); scr[kk * 33 + (lane & 31)] = W[(size_t)(k0 + kk) * N + n0 + (lane & 31)]; }
.LBB0_409:
	s_lshl_b32 s17, s12, 1
	s_lshl_b32 s20, s13, 1
	v_or_b32_e32 v101, s17, v5
	v_or_b32_e32 v104, s20, v0
	s_add_i32 s21, s17, 4
	s_add_i32 s22, s20, 4
	s_add_i32 s23, s17, 8
	s_add_i32 s24, s20, 8
	s_add_i32 s25, s17, 12
	s_add_i32 s26, s20, 12
	s_add_i32 s27, s17, 16
	s_add_i32 s28, s20, 16
	s_add_i32 s29, s17, 20
	s_add_i32 s30, s20, 20
	s_add_i32 s31, s17, 24
	s_add_i32 s33, s20, 24
	s_add_i32 s35, s17, 28
	s_add_i32 s36, s20, 28
	v_mad_u64_u32 v[114:115], s[18:19], v104, s37, v[22:23]
	v_mad_u64_u32 v[116:117], s[18:19], v101, s37, v[22:23]
	v_or_b32_e32 v101, s21, v5
	v_or_b32_e32 v104, s22, v0
	v_or_b32_e32 v113, s23, v5
	v_or_b32_e32 v122, s24, v0
	v_or_b32_e32 v128, s25, v5
	v_or_b32_e32 v126, s26, v0
	v_or_b32_e32 v132, s27, v5
	v_or_b32_e32 v130, s28, v0
	v_or_b32_e32 v136, s29, v5
	v_or_b32_e32 v134, s30, v0
	v_or_b32_e32 v140, s31, v5
	v_or_b32_e32 v138, s33, v0
	v_or_b32_e32 v144, s35, v5
	v_or_b32_e32 v142, s36, v0
	v_mad_u64_u32 v[118:119], s[18:19], v104, s37, v[22:23]
	v_mad_u64_u32 v[120:121], s[18:19], v101, s37, v[22:23]
	v_mad_u64_u32 v[122:123], s[18:19], v122, s37, v[22:23]
	v_mad_u64_u32 v[124:125], s[18:19], v113, s37, v[22:23]
	v_mad_u64_u32 v[126:127], s[18:19], v126, s37, v[22:23]
	v_mad_u64_u32 v[128:129], s[18:19], v128, s37, v[22:23]
	v_mad_u64_u32 v[130:131], s[18:19], v130, s37, v[22:23]
	v_mad_u64_u32 v[132:133], s[18:19], v132, s37, v[22:23]
	v_mad_u64_u32 v[134:135], s[18:19], v134, s37, v[22:23]
	v_mad_u64_u32 v[136:137], s[18:19], v136, s37, v[22:23]
	v_mad_u64_u32 v[138:139], s[18:19], v138, s37, v[22:23]
	v_mad_u64_u32 v[140:141], s[18:19], v140, s37, v[22:23]
	v_mad_u64_u32 v[142:143], s[18:19], v142, s37, v[22:23]
	v_mad_u64_u32 v[144:145], s[18:19], v144, s37, v[22:23]
	global_load_dword v101, v[114:115], off
	global_load_dword v104, v[116:117], off
	global_load_dword v113, v[118:119], off
	global_load_dword v146, v[120:121], off
	global_load_dword v147, v[122:123], off
	global_load_dword v148, v[124:125], off
	global_load_dword v149, v[126:127], off
	global_load_dword v150, v[128:129], off
	global_load_dword v151, v[130:131], off
	global_load_dword v152, v[132:133], off
	global_load_dword v153, v[134:135], off
	global_load_dword v154, v[136:137], off
	global_load_dword v155, v[138:139], off
	global_load_dword v156, v[140:141], off
	global_load_dword v157, v[142:143], off
	global_load_dword v158, v[144:145], off
	v_or_b32_e32 v116, s17, v3
	v_or_b32_e32 v114, s20, v2
	s_add_i32 s13, s13, 16
	s_add_i32 s12, s12, 16
	s_add_i32 s16, s16, -16
	v_mad_u64_u32 v[114:115], s[18:19], v114, s1, v[6:7]
	v_mad_u64_u32 v[116:117], s[18:19], v116, s1, v[6:7]
	v_or_b32_e32 v115, s21, v3
	v_or_b32_e32 v117, s22, v2
	v_or_b32_e32 v124, s23, v3
	v_or_b32_e32 v122, s24, v2
	v_or_b32_e32 v128, s25, v3
	v_or_b32_e32 v126, s26, v2
	v_or_b32_e32 v132, s27, v3
	v_or_b32_e32 v130, s28, v2
	v_or_b32_e32 v136, s29, v3
	v_or_b32_e32 v134, s30, v2
	v_or_b32_e32 v140, s31, v3
	v_or_b32_e32 v138, s33, v2
	v_or_b32_e32 v144, s35, v3
	v_or_b32_e32 v142, s36, v2
	s_cmp_lg_u32 s16, 0
	v_mad_u64_u32 v[118:119], s[18:19], v117, s1, v[6:7]
	v_mad_u64_u32 v[120:121], s[18:19], v115, s1, v[6:7]
	v_mad_u64_u32 v[122:123], s[18:19], v122, s1, v[6:7]
	v_mad_u64_u32 v[124:125], s[18:19], v124, s1, v[6:7]
	v_mad_u64_u32 v[126:127], s[18:19], v126, s1, v[6:7]
	v_mad_u64_u32 v[128:129], s[18:19], v128, s1, v[6:7]
	v_mad_u64_u32 v[130:131], s[18:19], v130, s1, v[6:7]
	v_mad_u64_u32 v[132:133], s[18:19], v132, s1, v[6:7]
	v_mad_u64_u32 v[134:135], s[18:19], v134, s1, v[6:7]
	v_mad_u64_u32 v[136:137], s[18:19], v136, s1, v[6:7]
	v_mad_u64_u32 v[138:139], s[18:19], v138, s1, v[6:7]
	v_mad_u64_u32 v[140:141], s[18:19], v140, s1, v[6:7]
	v_mad_u64_u32 v[142:143], s[18:19], v142, s1, v[6:7]
	v_mad_u64_u32 v[144:145], s[18:19], v144, s1, v[6:7]
	s_lshl_b32 s17, s12, 1
	s_lshl_b32 s20, s13, 1
	v_or_b32_e32 v21, s17, v5
	v_or_b32_e32 v24, s20, v0
	s_add_i32 s21, s17, 4
	s_add_i32 s22, s20, 4
	s_add_i32 s23, s17, 8
	s_add_i32 s24, s20, 8
	s_add_i32 s25, s17, 12
	s_add_i32 s26, s20, 12
	s_add_i32 s27, s17, 16
	s_add_i32 s28, s20, 16
	s_add_i32 s29, s17, 20
	s_add_i32 s30, s20, 20
	s_add_i32 s31, s17, 24
	s_add_i32 s33, s20, 24
	s_add_i32 s35, s17, 28
	s_add_i32 s36, s20, 28
	v_mad_u64_u32 v[34:35], s[18:19], v24, s37, v[22:23]
	v_mad_u64_u32 v[36:37], s[18:19], v21, s37, v[22:23]
	v_or_b32_e32 v21, s21, v5
	v_or_b32_e32 v24, s22, v0
	v_or_b32_e32 v33, s23, v5
	v_or_b32_e32 v42, s24, v0
	v_or_b32_e32 v48, s25, v5
	v_or_b32_e32 v46, s26, v0
	v_or_b32_e32 v52, s27, v5
	v_or_b32_e32 v50, s28, v0
	v_or_b32_e32 v56, s29, v5
	v_or_b32_e32 v54, s30, v0
	v_or_b32_e32 v60, s31, v5
	v_or_b32_e32 v58, s33, v0
	v_or_b32_e32 v64, s35, v5
	v_or_b32_e32 v62, s36, v0
	v_mad_u64_u32 v[38:39], s[18:19], v24, s37, v[22:23]
	v_mad_u64_u32 v[40:41], s[18:19], v21, s37, v[22:23]
	v_mad_u64_u32 v[42:43], s[18:19], v42, s37, v[22:23]
	v_mad_u64_u32 v[44:45], s[18:19], v33, s37, v[22:23]
	v_mad_u64_u32 v[46:47], s[18:19], v46, s37, v[22:23]
	v_mad_u64_u32 v[48:49], s[18:19], v48, s37, v[22:23]
	v_mad_u64_u32 v[50:51], s[18:19], v50, s37, v[22:23]
	v_mad_u64_u32 v[52:53], s[18:19], v52, s37, v[22:23]
	v_mad_u64_u32 v[54:55], s[18:19], v54, s37, v[22:23]
	v_mad_u64_u32 v[56:57], s[18:19], v56, s37, v[22:23]
	v_mad_u64_u32 v[58:59], s[18:19], v58, s37, v[22:23]
	v_mad_u64_u32 v[60:61], s[18:19], v60, s37, v[22:23]
	v_mad_u64_u32 v[62:63], s[18:19], v62, s37, v[22:23]
	v_mad_u64_u32 v[64:65], s[18:19], v64, s37, v[22:23]
	global_load_dword v21, v[34:35], off
	global_load_dword v24, v[36:37], off
	global_load_dword v33, v[38:39], off
	global_load_dword v66, v[40:41], off
;     ...
; #pragma unroll 8
;     for (int i = 0; i < 32; ++i) { const int kk = 2 * i + (lane >> 5); scr[kk * 33 + (lane & 31)] = W[(size_t)(k0 + kk) * N + n0 + (lane & 31)]; }
	global_load_dword v67, v[42:43], off
	global_load_dword v68, v[44:45], off
	global_load_dword v69, v[46:47], off
	global_load_dword v70, v[48:49], off
	global_load_dword v71, v[50:51], off
	global_load_dword v72, v[52:53], off
	global_load_dword v73, v[54:55], off
	global_load_dword v74, v[56:57], off
	global_load_dword v75, v[58:59], off
	global_load_dword v76, v[60:61], off
	global_load_dword v77, v[62:63], off
	global_load_dword v78, v[64:65], off
	v_or_b32_e32 v36, s17, v3
	v_or_b32_e32 v34, s20, v2
	s_add_i32 s13, s13, 16
	s_add_i32 s12, s12, 16
	s_add_i32 s16, s16, -16
	v_mad_u64_u32 v[34:35], s[18:19], v34, s1, v[6:7]
	v_mad_u64_u32 v[36:37], s[18:19], v36, s1, v[6:7]
	v_or_b32_e32 v35, s21, v3
	v_or_b32_e32 v37, s22, v2
	v_or_b32_e32 v44, s23, v3
	v_or_b32_e32 v42, s24, v2
	v_or_b32_e32 v48, s25, v3
	v_or_b32_e32 v46, s26, v2
	v_or_b32_e32 v52, s27, v3
	v_or_b32_e32 v50, s28, v2
	v_or_b32_e32 v56, s29, v3
	v_or_b32_e32 v54, s30, v2
	v_or_b32_e32 v60, s31, v3
	v_or_b32_e32 v58, s33, v2
	v_or_b32_e32 v64, s35, v3
	v_or_b32_e32 v62, s36, v2
	s_cmp_lg_u32 s16, 0
	v_mad_u64_u32 v[38:39], s[18:19], v37, s1, v[6:7]
	v_mad_u64_u32 v[40:41], s[18:19], v35, s1, v[6:7]
	v_mad_u64_u32 v[42:43], s[18:19], v42, s1, v[6:7]
	v_mad_u64_u32 v[44:45], s[18:19], v44, s1, v[6:7]
	v_mad_u64_u32 v[46:47], s[18:19], v46, s1, v[6:7]
	v_mad_u64_u32 v[48:49], s[18:19], v48, s1, v[6:7]
	v_mad_u64_u32 v[50:51], s[18:19], v50, s1, v[6:7]
	v_mad_u64_u32 v[52:53], s[18:19], v52, s1, v[6:7]
	v_mad_u64_u32 v[54:55], s[18:19], v54, s1, v[6:7]
	v_mad_u64_u32 v[56:57], s[18:19], v56, s1, v[6:7]
	v_mad_u64_u32 v[58:59], s[18:19], v58, s1, v[6:7]
	v_mad_u64_u32 v[60:61], s[18:19], v60, s1, v[6:7]
	v_mad_u64_u32 v[62:63], s[18:19], v62, s1, v[6:7]
	v_mad_u64_u32 v[64:65], s[18:19], v64, s1, v[6:7]
	s_waitcnt vmcnt(31)
	ds_write_b32 v114, v101
	s_waitcnt vmcnt(30)
	ds_write_b32 v116, v104
	s_waitcnt vmcnt(29)
	ds_write_b32 v118, v113
	s_waitcnt vmcnt(28)
	ds_write_b32 v120, v146
	s_waitcnt vmcnt(27)
	ds_write_b32 v122, v147
	s_waitcnt vmcnt(26)
	ds_write_b32 v124, v148
	s_waitcnt vmcnt(25)
	ds_write_b32 v126, v149
	s_waitcnt vmcnt(24)
	ds_write_b32 v128, v150
	s_waitcnt vmcnt(23)
	ds_write_b32 v130, v151
	s_waitcnt vmcnt(22)
	ds_write_b32 v132, v152
	s_waitcnt vmcnt(21)
	ds_write_b32 v134, v153
	s_waitcnt vmcnt(20)
	ds_write_b32 v136, v154
	s_waitcnt vmcnt(19)
	ds_write_b32 v138, v155
	s_waitcnt vmcnt(18)
	ds_write_b32 v140, v156
	s_waitcnt vmcnt(17)
	ds_write_b32 v142, v157
	s_waitcnt vmcnt(16)
	ds_write_b32 v144, v158
	s_waitcnt vmcnt(15)
	ds_write_b32 v34, v21
	s_waitcnt vmcnt(14)
	ds_write_b32 v36, v24
	s_waitcnt vmcnt(13)
	ds_write_b32 v38, v33
	s_waitcnt vmcnt(12)
	ds_write_b32 v40, v66
	s_waitcnt vmcnt(11)
	ds_write_b32 v42, v67
	s_waitcnt vmcnt(10)
	ds_write_b32 v44, v68
	s_waitcnt vmcnt(9)
	ds_write_b32 v46, v69
	s_waitcnt vmcnt(8)
	ds_write_b32 v48, v70
	s_waitcnt vmcnt(7)
	ds_write_b32 v50, v71
	s_waitcnt vmcnt(6)
	ds_write_b32 v52, v72
	s_waitcnt vmcnt(5)
	ds_write_b32 v54, v73
	s_waitcnt vmcnt(4)
	ds_write_b32 v56, v74
	s_waitcnt vmcnt(3)
	ds_write_b32 v58, v75
	s_waitcnt vmcnt(2)
	ds_write_b32 v60, v76
	s_waitcnt vmcnt(1)
	ds_write_b32 v62, v77
	s_waitcnt vmcnt(0)
	ds_write_b32 v64, v78
	s_waitcnt lgkmcnt(0)
	ds_read2_b32 v[22:23], v25 offset1:8
	ds_read2_b32 v[40:41], v25 offset0:33 offset1:41
	ds_read2_b32 v[42:43], v25 offset0:66 offset1:74
	ds_read2_b32 v[44:45], v25 offset0:99 offset1:107
	ds_read2_b32 v[46:47], v25 offset0:132 offset1:140
	s_waitcnt lgkmcnt(4)
	v_bfe_u32 v0, v22, 16, 1
	v_add3_u32 v0, v22, v0, s85
	s_waitcnt lgkmcnt(3)
	v_bfe_u32 v5, v40, 16, 1
	v_lshrrev_b32_e32 v0, 16, v0
	v_add3_u32 v5, v40, v5, s85
	ds_read2_b32 v[48:49], v25 offset0:165 offset1:173
	v_and_or_b32 v34, v5, s3, v0
	s_waitcnt lgkmcnt(3)
	v_bfe_u32 v0, v42, 16, 1
	s_and_b32 s12, 0xffff, s11
	v_add3_u32 v0, v42, v0, s85
	s_waitcnt lgkmcnt(2)
	v_bfe_u32 v5, v44, 16, 1
	ds_read2_b32 v[50:51], v25 offset0:198 offset1:206
	s_mul_i32 s13, s12, 0xaaab
	v_lshrrev_b32_e32 v0, 16, v0
	v_add3_u32 v5, v44, v5, s85
	ds_read2_b32 v[52:53], v25 offset0:231 offset1:239
	s_lshr_b32 s13, s13, 23
	v_and_or_b32 v35, v5, s3, v0
	s_waitcnt lgkmcnt(3)
; #define GAS __attribute__((address_space(1)))
; #define LAS __attribute__((address_space(3)))
; #define LDS_WAIT() asm volatile("s_waitcnt lgkmcnt(0)" ::: "memory")
; __device__ __forceinline__ unsigned pk2(float lo, float hi) { return f2bf(lo) | (f2bf(hi) << 16); }
;     ...
;     const int c = lane & 7;
; #pragma unroll
;     for (int j = 0; j < 4; ++j) { const int n = (lane >> 3) + 8 * j; const LAS float* s = scr + (8 * c) * 33 + n;
;         v4u o; o.x = pk2(s[0 * 33], s[1 * 33]); o.y = pk2(s[2 * 33], s[3 * 33]); o.z = pk2(s[4 * 33], s[5 * 33]); o.w = pk2(s[6 * 33], s[7 * 33]);
;         const int nr = pg ? (8 * ((n >> 2) & 3) + 4 * (n >> 4) + (n & 3)) : n;
;         *(GAS v4u*)(WT + (size_t)(n0 + nr) * K + k0 + 8 * c) = o; }
;     LDS_WAIT(); asm volatile("" ::: "memory");
	v_bfe_u32 v0, v46, 16, 1
	s_mulk_i32 s13, 0xc0
	v_add3_u32 v0, v46, v0, s85
	s_waitcnt lgkmcnt(2)
	v_bfe_u32 v5, v48, 16, 1
	s_sub_i32 s11, s11, s13
	v_lshrrev_b32_e32 v0, 16, v0
	v_add3_u32 v5, v48, v5, s85
	s_and_b32 s11, s11, 0xffff
	v_and_or_b32 v36, v5, s3, v0
	s_waitcnt lgkmcnt(1)
	v_bfe_u32 v0, v50, 16, 1
	s_cmpk_gt_u32 s11, 0x7f
	v_add3_u32 v0, v50, v0, s85
	s_waitcnt lgkmcnt(0)
	v_bfe_u32 v5, v52, 16, 1
	s_cselect_b64 vcc, -1, 0
	v_lshrrev_b32_e32 v0, 16, v0
	v_add3_u32 v5, v52, v5, s85
	s_and_b32 s10, 0xffff, s10
	v_and_or_b32 v37, v5, s3, v0
	v_cndmask_b32_e32 v0, v7, v29, vcc
	s_lshl_b32 s78, s10, 1
	v_or_b32_e32 v0, s12, v0
	v_lshl_add_u64 v[38:39], v[10:11], 0, s[78:79]
	v_lshlrev_b32_e32 v0, 10, v0
	v_lshl_add_u64 v[54:55], v[38:39], 0, v[0:1]
	v_bfe_u32 v0, v23, 16, 1
	v_add3_u32 v0, v23, v0, s85
	v_bfe_u32 v5, v41, 16, 1
	v_lshrrev_b32_e32 v0, 16, v0
	v_add3_u32 v5, v41, v5, s85
	global_store_dwordx4 v[54:55], v[34:37], off
	ds_read2_b32 v[22:23], v25 offset0:16 offset1:24
	s_nop 0
	v_and_or_b32 v34, v5, s3, v0
	v_bfe_u32 v0, v43, 16, 1
	v_add3_u32 v0, v43, v0, s85
	v_bfe_u32 v5, v45, 16, 1
	v_lshrrev_b32_e32 v0, 16, v0
	v_add3_u32 v5, v45, v5, s85
	v_and_or_b32 v35, v5, s3, v0
	v_bfe_u32 v0, v47, 16, 1
	v_add3_u32 v0, v47, v0, s85
	v_bfe_u32 v5, v49, 16, 1
	v_lshrrev_b32_e32 v0, 16, v0
	v_add3_u32 v5, v49, v5, s85
	v_and_or_b32 v36, v5, s3, v0
	v_bfe_u32 v0, v51, 16, 1
	v_add3_u32 v0, v51, v0, s85
	v_bfe_u32 v5, v53, 16, 1
	v_lshrrev_b32_e32 v0, 16, v0
	v_add3_u32 v5, v53, v5, s85
	v_and_or_b32 v37, v5, s3, v0
	v_cndmask_b32_e32 v0, v26, v30, vcc
	v_or_b32_e32 v0, s12, v0
	v_lshlrev_b32_e32 v0, 10, v0
	v_lshl_add_u64 v[40:41], v[38:39], 0, v[0:1]
	global_store_dwordx4 v[40:41], v[34:37], off
	ds_read2_b32 v[40:41], v25 offset0:49 offset1:57
	ds_read2_b32 v[42:43], v25 offset0:82 offset1:90
	ds_read2_b32 v[44:45], v25 offset0:115 offset1:123
	s_waitcnt lgkmcnt(3)
	v_bfe_u32 v0, v22, 16, 1
	v_add3_u32 v0, v22, v0, s85
	s_waitcnt lgkmcnt(2)
	v_bfe_u32 v5, v40, 16, 1
	ds_read2_b32 v[46:47], v25 offset0:148 offset1:156
	v_lshrrev_b32_e32 v0, 16, v0
	v_add3_u32 v5, v40, v5, s85
	ds_read2_b32 v[48:49], v25 offset0:181 offset1:189
	v_and_or_b32 v34, v5, s3, v0
	s_waitcnt lgkmcnt(3)
	v_bfe_u32 v0, v42, 16, 1
	v_add3_u32 v0, v42, v0, s85
	s_waitcnt lgkmcnt(2)
	v_bfe_u32 v5, v44, 16, 1
	ds_read2_b32 v[50:51], v25 offset0:214 offset1:222
	v_lshrrev_b32_e32 v0, 16, v0
	v_add3_u32 v5, v44, v5, s85
	ds_read2_b32 v[52:53], v25 offset0:247 offset1:255
	v_and_or_b32 v35, v5, s3, v0
	s_waitcnt lgkmcnt(3)
	v_bfe_u32 v0, v46, 16, 1
	v_add3_u32 v0, v46, v0, s85
	s_waitcnt lgkmcnt(2)
	v_bfe_u32 v5, v48, 16, 1
	v_lshrrev_b32_e32 v0, 16, v0
	v_add3_u32 v5, v48, v5, s85
	v_and_or_b32 v36, v5, s3, v0
	s_waitcnt lgkmcnt(1)
	v_bfe_u32 v0, v50, 16, 1
	v_add3_u32 v0, v50, v0, s85
	s_waitcnt lgkmcnt(0)
	v_bfe_u32 v5, v52, 16, 1
	v_lshrrev_b32_e32 v0, 16, v0
	v_add3_u32 v5, v52, v5, s85
	v_and_or_b32 v37, v5, s3, v0
	v_cndmask_b32_e32 v0, v27, v31, vcc
	v_or_b32_e32 v0, s12, v0
	v_lshlrev_b32_e32 v0, 10, v0
	v_lshl_add_u64 v[54:55], v[38:39], 0, v[0:1]
	v_bfe_u32 v0, v23, 16, 1
	v_add3_u32 v0, v23, v0, s85
	v_bfe_u32 v5, v41, 16, 1
	v_lshrrev_b32_e32 v0, 16, v0
	v_add3_u32 v5, v41, v5, s85
	global_store_dwordx4 v[54:55], v[34:37], off
	s_nop 1
	v_and_or_b32 v34, v5, s3, v0
	v_bfe_u32 v0, v43, 16, 1
	v_add3_u32 v0, v43, v0, s85
	v_bfe_u32 v5, v45, 16, 1
	v_lshrrev_b32_e32 v0, 16, v0
	v_add3_u32 v5, v45, v5, s85
	v_and_or_b32 v35, v5, s3, v0
	v_bfe_u32 v0, v47, 16, 1
	v_add3_u32 v0, v47, v0, s85
	v_bfe_u32 v5, v49, 16, 1
	v_lshrrev_b32_e32 v0, 16, v0
	v_add3_u32 v5, v49, v5, s85
	v_and_or_b32 v36, v5, s3, v0
	v_bfe_u32 v0, v51, 16, 1
	v_add3_u32 v0, v51, v0, s85
	v_bfe_u32 v5, v53, 16, 1
	v_lshrrev_b32_e32 v0, 16, v0
	v_add3_u32 v5, v53, v5, s85
	v_and_or_b32 v37, v5, s3, v0
	v_cndmask_b32_e32 v0, v28, v32, vcc
	v_or_b32_e32 v0, s12, v0
	v_lshlrev_b32_e32 v0, 10, v0
	v_lshl_add_u64 v[22:23], v[38:39], 0, v[0:1]
	global_store_dwordx4 v[22:23], v[34:37], off
	s_waitcnt lgkmcnt(0)

;     ...
; #pragma unroll 8
;     for (int i = 0; i < 32; ++i) { const int kk = 2 * i + (lane >> 5); scr[kk * 33 + (lane & 31)] = W[(size_t)(k0 + kk) * N + n0 + (lane & 31)]; }
.LBB0_420:
	v_mov_b32_e32 v81, v1
	s_lshl_b32 s18, s13, 1
	s_lshl_b32 s19, s16, 1
	v_or_b32_e32 v80, s19, v24
	s_add_i32 s20, s18, 4
	s_add_i32 s21, s19, 4
	v_mov_b32_e32 v117, v1
	s_add_i32 s23, s19, 8
	v_lshlrev_b64 v[130:131], 13, v[80:81]
	v_or_b32_e32 v116, s20, v5
	v_or_b32_e32 v80, s21, v24
	v_mov_b32_e32 v115, v1
	v_or_b32_e32 v114, s18, v5
	s_add_i32 s25, s19, 12
	v_lshlrev_b64 v[116:117], 13, v[116:117]
	v_lshlrev_b64 v[132:133], 13, v[80:81]
	v_or_b32_e32 v80, s23, v24
	s_add_i32 s22, s18, 8
	s_add_i32 s24, s18, 12
	s_add_i32 s27, s19, 16
	v_lshlrev_b64 v[114:115], 13, v[114:115]
	v_lshl_add_u64 v[130:131], v[22:23], 0, v[130:131]
	v_lshl_add_u64 v[116:117], v[22:23], 0, v[116:117]
	v_lshlrev_b64 v[134:135], 13, v[80:81]
	v_or_b32_e32 v80, s25, v24
	v_mov_b32_e32 v119, v1
	v_mov_b32_e32 v121, v1
	s_add_i32 s29, s19, 20
	v_or_b32_e32 v118, s22, v5
	v_or_b32_e32 v120, s24, v5
	v_lshl_add_u64 v[114:115], v[22:23], 0, v[114:115]
	v_lshl_add_u64 v[132:133], v[22:23], 0, v[132:133]
	global_load_dword v101, v[130:131], off
	global_load_dword v113, v[114:115], off
	global_load_dword v146, v[132:133], off
	global_load_dword v147, v[116:117], off
	v_lshlrev_b64 v[116:117], 13, v[80:81]
	v_or_b32_e32 v80, s27, v24
	s_add_i32 s26, s18, 16
	s_add_i32 s28, s18, 20
	s_add_i32 s31, s19, 24
	v_lshlrev_b64 v[118:119], 13, v[118:119]
	v_lshlrev_b64 v[120:121], 13, v[120:121]
	v_lshl_add_u64 v[114:115], v[22:23], 0, v[134:135]
	v_lshl_add_u64 v[116:117], v[22:23], 0, v[116:117]
	v_lshlrev_b64 v[130:131], 13, v[80:81]
	v_or_b32_e32 v80, s29, v24
	v_mov_b32_e32 v123, v1
	v_mov_b32_e32 v125, v1
	s_add_i32 s30, s18, 24
	s_add_i32 s33, s18, 28
	s_add_i32 s35, s19, 28
	v_or_b32_e32 v122, s26, v5
	v_or_b32_e32 v124, s28, v5
	v_lshl_add_u64 v[118:119], v[22:23], 0, v[118:119]
	v_lshl_add_u64 v[120:121], v[22:23], 0, v[120:121]
	global_load_dword v148, v[114:115], off
	global_load_dword v149, v[118:119], off
	global_load_dword v150, v[116:117], off
	global_load_dword v151, v[120:121], off
	v_lshlrev_b64 v[116:117], 13, v[80:81]
	v_or_b32_e32 v80, s31, v24
	v_mov_b32_e32 v127, v1
	v_mov_b32_e32 v129, v1
	v_or_b32_e32 v126, s30, v5
	v_or_b32_e32 v128, s33, v5
	v_lshlrev_b64 v[122:123], 13, v[122:123]
	v_lshlrev_b64 v[124:125], 13, v[124:125]
	v_lshl_add_u64 v[114:115], v[22:23], 0, v[130:131]
	v_lshl_add_u64 v[116:117], v[22:23], 0, v[116:117]
	v_lshlrev_b64 v[118:119], 13, v[80:81]
	v_or_b32_e32 v80, s35, v24
	v_lshlrev_b64 v[126:127], 13, v[126:127]
	v_lshlrev_b64 v[128:129], 13, v[128:129]
	v_lshl_add_u64 v[122:123], v[22:23], 0, v[122:123]
	v_lshl_add_u64 v[124:125], v[22:23], 0, v[124:125]
	global_load_dword v152, v[114:115], off
	global_load_dword v153, v[122:123], off
	global_load_dword v154, v[116:117], off
	global_load_dword v155, v[124:125], off
	v_lshl_add_u64 v[114:115], v[22:23], 0, v[118:119]
	v_lshlrev_b64 v[116:117], 13, v[80:81]
	v_lshl_add_u64 v[126:127], v[22:23], 0, v[126:127]
	v_lshl_add_u64 v[128:129], v[22:23], 0, v[128:129]
	v_lshl_add_u64 v[116:117], v[22:23], 0, v[116:117]
	global_load_dword v80, v[114:115], off
	global_load_dword v156, v[126:127], off
	global_load_dword v157, v[116:117], off
	global_load_dword v158, v[128:129], off
	v_or_b32_e32 v116, s18, v3
	v_or_b32_e32 v114, s19, v2
	s_add_i32 s16, s16, 16
	s_add_i32 s13, s13, 16
	s_add_i32 s17, s17, -16
	v_mad_u64_u32 v[114:115], s[18:19], v114, s1, v[6:7]
	v_mad_u64_u32 v[116:117], s[18:19], v116, s1, v[6:7]
	v_or_b32_e32 v115, s20, v3
	v_or_b32_e32 v117, s21, v2
	v_or_b32_e32 v124, s22, v3
	v_or_b32_e32 v122, s23, v2
	v_or_b32_e32 v128, s24, v3
	v_or_b32_e32 v126, s25, v2
	v_or_b32_e32 v132, s26, v3
	v_or_b32_e32 v130, s27, v2
	v_or_b32_e32 v136, s28, v3
	v_or_b32_e32 v134, s29, v2
	v_or_b32_e32 v140, s30, v3
	v_or_b32_e32 v138, s31, v2
	v_or_b32_e32 v144, s33, v3
	v_or_b32_e32 v142, s35, v2
	s_cmp_lg_u32 s17, 0
	v_mad_u64_u32 v[118:119], s[18:19], v117, s1, v[6:7]
	v_mad_u64_u32 v[120:121], s[18:19], v115, s1, v[6:7]
	v_mad_u64_u32 v[122:123], s[18:19], v122, s1, v[6:7]
	v_mad_u64_u32 v[124:125], s[18:19], v124, s1, v[6:7]
	v_mad_u64_u32 v[126:127], s[18:19], v126, s1, v[6:7]
	v_mad_u64_u32 v[128:129], s[18:19], v128, s1, v[6:7]
	v_mad_u64_u32 v[130:131], s[18:19], v130, s1, v[6:7]
	v_mad_u64_u32 v[132:133], s[18:19], v132, s1, v[6:7]
	v_mad_u64_u32 v[134:135], s[18:19], v134, s1, v[6:7]
	v_mad_u64_u32 v[136:137], s[18:19], v136, s1, v[6:7]
	v_mad_u64_u32 v[138:139], s[18:19], v138, s1, v[6:7]
	v_mad_u64_u32 v[140:141], s[18:19], v140, s1, v[6:7]
	v_mad_u64_u32 v[142:143], s[18:19], v142, s1, v[6:7]
	v_mad_u64_u32 v[144:145], s[18:19], v144, s1, v[6:7]
	s_lshl_b32 s18, s13, 1
	s_lshl_b32 s19, s16, 1
	v_or_b32_e32 v0, s19, v24
	s_add_i32 s20, s18, 4
	s_add_i32 s21, s19, 4
	v_mov_b32_e32 v37, v1
	s_add_i32 s23, s19, 8
	v_lshlrev_b64 v[50:51], 13, v[0:1]
	v_or_b32_e32 v36, s20, v5
	v_or_b32_e32 v0, s21, v24
	v_mov_b32_e32 v35, v1
	v_or_b32_e32 v34, s18, v5
	s_add_i32 s25, s19, 12
	v_lshlrev_b64 v[36:37], 13, v[36:37]
	v_lshlrev_b64 v[52:53], 13, v[0:1]
	v_or_b32_e32 v0, s23, v24
	s_add_i32 s22, s18, 8
	s_add_i32 s24, s18, 12
	s_add_i32 s27, s19, 16
	v_lshlrev_b64 v[34:35], 13, v[34:35]
	v_lshl_add_u64 v[50:51], v[22:23], 0, v[50:51]
	v_lshl_add_u64 v[36:37], v[22:23], 0, v[36:37]
	v_lshlrev_b64 v[54:55], 13, v[0:1]
	v_or_b32_e32 v0, s25, v24
	v_mov_b32_e32 v39, v1
	v_mov_b32_e32 v41, v1
	s_add_i32 s29, s19, 20
	v_or_b32_e32 v38, s22, v5
	v_or_b32_e32 v40, s24, v5
	v_lshl_add_u64 v[34:35], v[22:23], 0, v[34:35]
	v_lshl_add_u64 v[52:53], v[22:23], 0, v[52:53]
	global_load_dword v21, v[50:51], off
	global_load_dword v33, v[34:35], off
	global_load_dword v66, v[52:53], off
;     ...
; #pragma unroll 8
;     for (int i = 0; i < 32; ++i) { const int kk = 2 * i + (lane >> 5); scr[kk * 33 + (lane & 31)] = W[(size_t)(k0 + kk) * N + n0 + (lane & 31)]; }
	global_load_dword v67, v[36:37], off
	v_lshlrev_b64 v[36:37], 13, v[0:1]
	v_or_b32_e32 v0, s27, v24
	s_add_i32 s26, s18, 16
	s_add_i32 s28, s18, 20
	s_add_i32 s31, s19, 24
	v_lshlrev_b64 v[38:39], 13, v[38:39]
	v_lshlrev_b64 v[40:41], 13, v[40:41]
	v_lshl_add_u64 v[34:35], v[22:23], 0, v[54:55]
	v_lshl_add_u64 v[36:37], v[22:23], 0, v[36:37]
	v_lshlrev_b64 v[50:51], 13, v[0:1]
	v_or_b32_e32 v0, s29, v24
	v_mov_b32_e32 v43, v1
	v_mov_b32_e32 v45, v1
	s_add_i32 s30, s18, 24
	s_add_i32 s33, s18, 28
	s_add_i32 s35, s19, 28
	v_or_b32_e32 v42, s26, v5
	v_or_b32_e32 v44, s28, v5
	v_lshl_add_u64 v[38:39], v[22:23], 0, v[38:39]
	v_lshl_add_u64 v[40:41], v[22:23], 0, v[40:41]
	global_load_dword v68, v[34:35], off
	global_load_dword v69, v[38:39], off
	global_load_dword v70, v[36:37], off
	global_load_dword v71, v[40:41], off
	v_lshlrev_b64 v[36:37], 13, v[0:1]
	v_or_b32_e32 v0, s31, v24
	v_mov_b32_e32 v47, v1
	v_mov_b32_e32 v49, v1
	v_or_b32_e32 v46, s30, v5
	v_or_b32_e32 v48, s33, v5
	v_lshlrev_b64 v[42:43], 13, v[42:43]
	v_lshlrev_b64 v[44:45], 13, v[44:45]
	v_lshl_add_u64 v[34:35], v[22:23], 0, v[50:51]
	v_lshl_add_u64 v[36:37], v[22:23], 0, v[36:37]
	v_lshlrev_b64 v[38:39], 13, v[0:1]
	v_or_b32_e32 v0, s35, v24
	v_lshlrev_b64 v[46:47], 13, v[46:47]
	v_lshlrev_b64 v[48:49], 13, v[48:49]
	v_lshl_add_u64 v[42:43], v[22:23], 0, v[42:43]
	v_lshl_add_u64 v[44:45], v[22:23], 0, v[44:45]
	global_load_dword v72, v[34:35], off
	global_load_dword v73, v[42:43], off
	global_load_dword v74, v[36:37], off
	global_load_dword v75, v[44:45], off
	v_lshl_add_u64 v[34:35], v[22:23], 0, v[38:39]
	v_lshlrev_b64 v[36:37], 13, v[0:1]
	v_lshl_add_u64 v[46:47], v[22:23], 0, v[46:47]
	v_lshl_add_u64 v[48:49], v[22:23], 0, v[48:49]
	v_lshl_add_u64 v[36:37], v[22:23], 0, v[36:37]
	global_load_dword v0, v[34:35], off
	global_load_dword v76, v[46:47], off
	global_load_dword v77, v[36:37], off
	global_load_dword v78, v[48:49], off
	v_or_b32_e32 v36, s18, v3
	v_or_b32_e32 v34, s19, v2
	s_add_i32 s16, s16, 16
	s_add_i32 s13, s13, 16
	s_add_i32 s17, s17, -16
	v_mad_u64_u32 v[34:35], s[18:19], v34, s1, v[6:7]
	v_mad_u64_u32 v[36:37], s[18:19], v36, s1, v[6:7]
	v_or_b32_e32 v35, s20, v3
	v_or_b32_e32 v37, s21, v2
	v_or_b32_e32 v44, s22, v3
	v_or_b32_e32 v42, s23, v2
	v_or_b32_e32 v48, s24, v3
	v_or_b32_e32 v46, s25, v2
	v_or_b32_e32 v52, s26, v3
	v_or_b32_e32 v50, s27, v2
	v_or_b32_e32 v56, s28, v3
	v_or_b32_e32 v54, s29, v2
	v_or_b32_e32 v60, s30, v3
	v_or_b32_e32 v58, s31, v2
	v_or_b32_e32 v64, s33, v3
	v_or_b32_e32 v62, s35, v2
	s_cmp_lg_u32 s17, 0
	v_mad_u64_u32 v[38:39], s[18:19], v37, s1, v[6:7]
	v_mad_u64_u32 v[40:41], s[18:19], v35, s1, v[6:7]
	v_mad_u64_u32 v[42:43], s[18:19], v42, s1, v[6:7]
	v_mad_u64_u32 v[44:45], s[18:19], v44, s1, v[6:7]
	v_mad_u64_u32 v[46:47], s[18:19], v46, s1, v[6:7]
	v_mad_u64_u32 v[48:49], s[18:19], v48, s1, v[6:7]
	v_mad_u64_u32 v[50:51], s[18:19], v50, s1, v[6:7]
	v_mad_u64_u32 v[52:53], s[18:19], v52, s1, v[6:7]
	v_mad_u64_u32 v[54:55], s[18:19], v54, s1, v[6:7]
	v_mad_u64_u32 v[56:57], s[18:19], v56, s1, v[6:7]
	v_mad_u64_u32 v[58:59], s[18:19], v58, s1, v[6:7]
	v_mad_u64_u32 v[60:61], s[18:19], v60, s1, v[6:7]
	v_mad_u64_u32 v[62:63], s[18:19], v62, s1, v[6:7]
	v_mad_u64_u32 v[64:65], s[18:19], v64, s1, v[6:7]
	s_waitcnt vmcnt(31)
	ds_write_b32 v114, v101
	s_waitcnt vmcnt(30)
	ds_write_b32 v116, v113
	s_waitcnt vmcnt(29)
	ds_write_b32 v118, v146
	s_waitcnt vmcnt(28)
	ds_write_b32 v120, v147
	s_waitcnt vmcnt(27)
	ds_write_b32 v122, v148
	s_waitcnt vmcnt(26)
	ds_write_b32 v124, v149
	s_waitcnt vmcnt(25)
	ds_write_b32 v126, v150
	s_waitcnt vmcnt(24)
	ds_write_b32 v128, v151
	s_waitcnt vmcnt(23)
	ds_write_b32 v130, v152
	s_waitcnt vmcnt(22)
	ds_write_b32 v132, v153
	s_waitcnt vmcnt(21)
	ds_write_b32 v134, v154
	s_waitcnt vmcnt(20)
	ds_write_b32 v136, v155
	s_waitcnt vmcnt(19)
	ds_write_b32 v138, v80
	s_waitcnt vmcnt(18)
	ds_write_b32 v140, v156
	s_waitcnt vmcnt(17)
	ds_write_b32 v142, v157
	s_waitcnt vmcnt(16)
	ds_write_b32 v144, v158
	s_waitcnt vmcnt(15)
	ds_write_b32 v34, v21
	s_waitcnt vmcnt(14)
	ds_write_b32 v36, v33
	s_waitcnt vmcnt(13)
	ds_write_b32 v38, v66
	s_waitcnt vmcnt(12)
	ds_write_b32 v40, v67
	s_waitcnt vmcnt(11)
	ds_write_b32 v42, v68
	s_waitcnt vmcnt(10)
	ds_write_b32 v44, v69
	s_waitcnt vmcnt(9)
	ds_write_b32 v46, v70
	s_waitcnt vmcnt(8)
	ds_write_b32 v48, v71
	s_waitcnt vmcnt(7)
	ds_write_b32 v50, v72
	s_waitcnt vmcnt(6)
	ds_write_b32 v52, v73
	s_waitcnt vmcnt(5)
	ds_write_b32 v54, v74
	s_waitcnt vmcnt(4)
	ds_write_b32 v56, v75
	s_waitcnt vmcnt(3)
	ds_write_b32 v58, v0
	s_waitcnt vmcnt(2)
	ds_write_b32 v60, v76
	s_waitcnt vmcnt(1)
	ds_write_b32 v62, v77
	s_waitcnt vmcnt(0)
	ds_write_b32 v64, v78
	s_waitcnt lgkmcnt(0)
; #define GAS __attribute__((address_space(1)))
; #define LAS __attribute__((address_space(3)))
; #define LDS_WAIT() asm volatile("s_waitcnt lgkmcnt(0)" ::: "memory")
; __device__ __forceinline__ unsigned pk2(float lo, float hi) { return f2bf(lo) | (f2bf(hi) << 16); }
;     ...
;     const int c = lane & 7;
; #pragma unroll
;     for (int j = 0; j < 4; ++j) { const int n = (lane >> 3) + 8 * j; const LAS float* s = scr + (8 * c) * 33 + n;
;         v4u o; o.x = pk2(s[0 * 33], s[1 * 33]); o.y = pk2(s[2 * 33], s[3 * 33]); o.z = pk2(s[4 * 33], s[5 * 33]); o.w = pk2(s[6 * 33], s[7 * 33]);
;         const int nr = pg ? (8 * ((n >> 2) & 3) + 4 * (n >> 4) + (n & 3)) : n;
;         *(GAS v4u*)(WT + (size_t)(n0 + nr) * K + k0 + 8 * c) = o; }
;     LDS_WAIT(); asm volatile("" ::: "memory");
	ds_read2_b32 v[22:23], v25 offset1:8
	ds_read2_b32 v[40:41], v25 offset0:33 offset1:41
	ds_read2_b32 v[42:43], v25 offset0:66 offset1:74
	ds_read2_b32 v[44:45], v25 offset0:99 offset1:107
	ds_read2_b32 v[46:47], v25 offset0:132 offset1:140
	s_waitcnt lgkmcnt(4)
	v_bfe_u32 v0, v22, 16, 1
	v_add3_u32 v0, v22, v0, s85
	s_waitcnt lgkmcnt(3)
	v_bfe_u32 v5, v40, 16, 1
	v_lshrrev_b32_e32 v0, 16, v0
	v_add3_u32 v5, v40, v5, s85
	ds_read2_b32 v[48:49], v25 offset0:165 offset1:173
	v_and_or_b32 v34, v5, s3, v0
	s_waitcnt lgkmcnt(3)
	v_bfe_u32 v0, v42, 16, 1
	v_add3_u32 v0, v42, v0, s85
	s_waitcnt lgkmcnt(2)
	v_bfe_u32 v5, v44, 16, 1
	ds_read2_b32 v[50:51], v25 offset0:198 offset1:206
	v_lshrrev_b32_e32 v0, 16, v0
	v_add3_u32 v5, v44, v5, s85
	ds_read2_b32 v[52:53], v25 offset0:231 offset1:239
	v_and_or_b32 v35, v5, s3, v0
	s_waitcnt lgkmcnt(3)
	v_bfe_u32 v0, v46, 16, 1
	s_and_b32 s78, s12, 0xfffff800
	v_add3_u32 v0, v46, v0, s85
	s_waitcnt lgkmcnt(2)
	v_bfe_u32 v5, v48, 16, 1
	s_lshl_b64 s[12:13], s[78:79], 12
	v_lshrrev_b32_e32 v0, 16, v0
	v_add3_u32 v5, v48, v5, s85
	s_add_u32 s12, s2, s12
	v_and_or_b32 v36, v5, s3, v0
	s_waitcnt lgkmcnt(1)
	v_bfe_u32 v0, v50, 16, 1
	s_addc_u32 s13, s15, s13
	s_lshl_b32 s11, s11, 1
	v_add3_u32 v0, v50, v0, s85
	s_waitcnt lgkmcnt(0)
	v_bfe_u32 v5, v52, 16, 1
	s_add_u32 s12, s12, s11
	v_lshrrev_b32_e32 v0, 16, v0
	v_add3_u32 v5, v52, v5, s85
	s_addc_u32 s13, s13, 0
	v_mov_b32_e32 v21, v1
	v_and_or_b32 v37, v5, s3, v0
	v_or_b32_e32 v0, s10, v7
	v_lshl_add_u64 v[38:39], s[12:13], 0, v[20:21]
	v_lshlrev_b32_e32 v0, 12, v0
	v_lshl_add_u64 v[54:55], v[38:39], 0, v[0:1]
	v_bfe_u32 v0, v23, 16, 1
	v_add3_u32 v0, v23, v0, s85
	v_bfe_u32 v5, v41, 16, 1
	v_lshrrev_b32_e32 v0, 16, v0
	v_add3_u32 v5, v41, v5, s85
	global_store_dwordx4 v[54:55], v[34:37], off
	ds_read2_b32 v[22:23], v25 offset0:16 offset1:24
	s_nop 0
	v_and_or_b32 v34, v5, s3, v0
	v_bfe_u32 v0, v43, 16, 1
	v_add3_u32 v0, v43, v0, s85
	v_bfe_u32 v5, v45, 16, 1
	v_lshrrev_b32_e32 v0, 16, v0
	v_add3_u32 v5, v45, v5, s85
	v_and_or_b32 v35, v5, s3, v0
	v_bfe_u32 v0, v47, 16, 1
	v_add3_u32 v0, v47, v0, s85
	v_bfe_u32 v5, v49, 16, 1
	v_lshrrev_b32_e32 v0, 16, v0
	v_add3_u32 v5, v49, v5, s85
	v_and_or_b32 v36, v5, s3, v0
	v_bfe_u32 v0, v51, 16, 1
	v_add3_u32 v0, v51, v0, s85
	v_bfe_u32 v5, v53, 16, 1
	v_lshrrev_b32_e32 v0, 16, v0
	v_add3_u32 v5, v53, v5, s85
	v_and_or_b32 v37, v5, s3, v0
	v_or_b32_e32 v0, s10, v26
	v_lshlrev_b32_e32 v0, 12, v0
	v_lshl_add_u64 v[40:41], v[38:39], 0, v[0:1]
	global_store_dwordx4 v[40:41], v[34:37], off
	ds_read2_b32 v[40:41], v25 offset0:49 offset1:57
	ds_read2_b32 v[42:43], v25 offset0:82 offset1:90
	ds_read2_b32 v[44:45], v25 offset0:115 offset1:123
	s_waitcnt lgkmcnt(3)
	v_bfe_u32 v0, v22, 16, 1
	v_add3_u32 v0, v22, v0, s85
	s_waitcnt lgkmcnt(2)
	v_bfe_u32 v5, v40, 16, 1
	ds_read2_b32 v[46:47], v25 offset0:148 offset1:156
	v_lshrrev_b32_e32 v0, 16, v0
	v_add3_u32 v5, v40, v5, s85
	ds_read2_b32 v[48:49], v25 offset0:181 offset1:189
	v_and_or_b32 v34, v5, s3, v0
	s_waitcnt lgkmcnt(3)
	v_bfe_u32 v0, v42, 16, 1
	v_add3_u32 v0, v42, v0, s85
	s_waitcnt lgkmcnt(2)
	v_bfe_u32 v5, v44, 16, 1
	ds_read2_b32 v[50:51], v25 offset0:214 offset1:222
	v_lshrrev_b32_e32 v0, 16, v0
	v_add3_u32 v5, v44, v5, s85
	ds_read2_b32 v[52:53], v25 offset0:247 offset1:255
	v_and_or_b32 v35, v5, s3, v0
	s_waitcnt lgkmcnt(3)
	v_bfe_u32 v0, v46, 16, 1
	v_add3_u32 v0, v46, v0, s85
	s_waitcnt lgkmcnt(2)
	v_bfe_u32 v5, v48, 16, 1
	v_lshrrev_b32_e32 v0, 16, v0
	v_add3_u32 v5, v48, v5, s85
	v_and_or_b32 v36, v5, s3, v0
	s_waitcnt lgkmcnt(1)
	v_bfe_u32 v0, v50, 16, 1
	v_add3_u32 v0, v50, v0, s85
	s_waitcnt lgkmcnt(0)
	v_bfe_u32 v5, v52, 16, 1
	v_lshrrev_b32_e32 v0, 16, v0
	v_add3_u32 v5, v52, v5, s85
	v_and_or_b32 v37, v5, s3, v0
	v_or_b32_e32 v0, s10, v27
	v_lshlrev_b32_e32 v0, 12, v0
	v_lshl_add_u64 v[54:55], v[38:39], 0, v[0:1]
	v_bfe_u32 v0, v23, 16, 1
	v_add3_u32 v0, v23, v0, s85
	v_bfe_u32 v5, v41, 16, 1
	v_lshrrev_b32_e32 v0, 16, v0
	v_add3_u32 v5, v41, v5, s85
	global_store_dwordx4 v[54:55], v[34:37], off
	s_nop 1
	v_and_or_b32 v34, v5, s3, v0
	v_bfe_u32 v0, v43, 16, 1
	v_add3_u32 v0, v43, v0, s85
	v_bfe_u32 v5, v45, 16, 1
	v_lshrrev_b32_e32 v0, 16, v0
	v_add3_u32 v5, v45, v5, s85
	v_and_or_b32 v35, v5, s3, v0
	v_bfe_u32 v0, v47, 16, 1
	v_add3_u32 v0, v47, v0, s85
	v_bfe_u32 v5, v49, 16, 1
	v_lshrrev_b32_e32 v0, 16, v0
	v_add3_u32 v5, v49, v5, s85
	v_and_or_b32 v36, v5, s3, v0
	v_bfe_u32 v0, v51, 16, 1
	v_add3_u32 v0, v51, v0, s85
	v_bfe_u32 v5, v53, 16, 1
	v_lshrrev_b32_e32 v0, 16, v0
	v_add3_u32 v5, v53, v5, s85
	v_and_or_b32 v37, v5, s3, v0
	v_or_b32_e32 v0, s10, v28
	v_lshlrev_b32_e32 v0, 12, v0
	v_lshl_add_u64 v[22:23], v[38:39], 0, v[0:1]
	global_store_dwordx4 v[22:23], v[34:37], off
	s_waitcnt lgkmcnt(0)

;     ...
; #pragma unroll 8
;     for (int i = 0; i < 32; ++i) { const int kk = 2 * i + (lane >> 5); scr[kk * 33 + (lane & 31)] = W[(size_t)(k0 + kk) * N + n0 + (lane & 31)]; }
.LBB0_425:
	s_lshl_b32 s17, s12, 1
	s_lshl_b32 s20, s13, 1
	v_or_b32_e32 v101, s17, v5
	v_or_b32_e32 v104, s20, v0
	s_add_i32 s21, s17, 4
	s_add_i32 s22, s20, 4
	s_add_i32 s23, s17, 8
	s_add_i32 s24, s20, 8
	s_add_i32 s25, s17, 12
	s_add_i32 s26, s20, 12
	s_add_i32 s27, s17, 16
	s_add_i32 s28, s20, 16
	s_add_i32 s29, s17, 20
	s_add_i32 s30, s20, 20
	s_add_i32 s31, s17, 24
	s_add_i32 s33, s20, 24
	s_add_i32 s35, s17, 28
	s_add_i32 s36, s20, 28
	v_mad_u64_u32 v[114:115], s[18:19], v104, s76, v[22:23]
	v_mad_u64_u32 v[116:117], s[18:19], v101, s76, v[22:23]
	v_or_b32_e32 v101, s21, v5
	v_or_b32_e32 v104, s22, v0
	v_or_b32_e32 v113, s23, v5
	v_or_b32_e32 v122, s24, v0
	v_or_b32_e32 v128, s25, v5
	v_or_b32_e32 v126, s26, v0
	v_or_b32_e32 v132, s27, v5
	v_or_b32_e32 v130, s28, v0
	v_or_b32_e32 v136, s29, v5
	v_or_b32_e32 v134, s30, v0
	v_or_b32_e32 v140, s31, v5
	v_or_b32_e32 v138, s33, v0
	v_or_b32_e32 v144, s35, v5
	v_or_b32_e32 v142, s36, v0
	v_mad_u64_u32 v[118:119], s[18:19], v104, s76, v[22:23]
	v_mad_u64_u32 v[120:121], s[18:19], v101, s76, v[22:23]
	v_mad_u64_u32 v[122:123], s[18:19], v122, s76, v[22:23]
	v_mad_u64_u32 v[124:125], s[18:19], v113, s76, v[22:23]
	v_mad_u64_u32 v[126:127], s[18:19], v126, s76, v[22:23]
	v_mad_u64_u32 v[128:129], s[18:19], v128, s76, v[22:23]
	v_mad_u64_u32 v[130:131], s[18:19], v130, s76, v[22:23]
	v_mad_u64_u32 v[132:133], s[18:19], v132, s76, v[22:23]
	v_mad_u64_u32 v[134:135], s[18:19], v134, s76, v[22:23]
	v_mad_u64_u32 v[136:137], s[18:19], v136, s76, v[22:23]
	v_mad_u64_u32 v[138:139], s[18:19], v138, s76, v[22:23]
	v_mad_u64_u32 v[140:141], s[18:19], v140, s76, v[22:23]
	v_mad_u64_u32 v[142:143], s[18:19], v142, s76, v[22:23]
	v_mad_u64_u32 v[144:145], s[18:19], v144, s76, v[22:23]
	global_load_dword v101, v[114:115], off
	global_load_dword v104, v[116:117], off
	global_load_dword v113, v[118:119], off
	global_load_dword v146, v[120:121], off
	global_load_dword v147, v[122:123], off
	global_load_dword v148, v[124:125], off
	global_load_dword v149, v[126:127], off
	global_load_dword v150, v[128:129], off
	global_load_dword v151, v[130:131], off
	global_load_dword v152, v[132:133], off
	global_load_dword v153, v[134:135], off
	global_load_dword v154, v[136:137], off
	global_load_dword v155, v[138:139], off
	global_load_dword v156, v[140:141], off
	global_load_dword v157, v[142:143], off
	global_load_dword v158, v[144:145], off
	v_or_b32_e32 v116, s17, v3
	v_or_b32_e32 v114, s20, v2
	s_add_i32 s13, s13, 16
	s_add_i32 s12, s12, 16
	s_add_i32 s16, s16, -16
	v_mad_u64_u32 v[114:115], s[18:19], v114, s1, v[6:7]
	v_mad_u64_u32 v[116:117], s[18:19], v116, s1, v[6:7]
	v_or_b32_e32 v115, s21, v3
	v_or_b32_e32 v117, s22, v2
	v_or_b32_e32 v124, s23, v3
	v_or_b32_e32 v122, s24, v2
	v_or_b32_e32 v128, s25, v3
	v_or_b32_e32 v126, s26, v2
	v_or_b32_e32 v132, s27, v3
	v_or_b32_e32 v130, s28, v2
	v_or_b32_e32 v136, s29, v3
	v_or_b32_e32 v134, s30, v2
	v_or_b32_e32 v140, s31, v3
	v_or_b32_e32 v138, s33, v2
	v_or_b32_e32 v144, s35, v3
	v_or_b32_e32 v142, s36, v2
	s_cmp_lg_u32 s16, 0
	v_mad_u64_u32 v[118:119], s[18:19], v117, s1, v[6:7]
	v_mad_u64_u32 v[120:121], s[18:19], v115, s1, v[6:7]
	v_mad_u64_u32 v[122:123], s[18:19], v122, s1, v[6:7]
	v_mad_u64_u32 v[124:125], s[18:19], v124, s1, v[6:7]
	v_mad_u64_u32 v[126:127], s[18:19], v126, s1, v[6:7]
	v_mad_u64_u32 v[128:129], s[18:19], v128, s1, v[6:7]
	v_mad_u64_u32 v[130:131], s[18:19], v130, s1, v[6:7]
	v_mad_u64_u32 v[132:133], s[18:19], v132, s1, v[6:7]
	v_mad_u64_u32 v[134:135], s[18:19], v134, s1, v[6:7]
	v_mad_u64_u32 v[136:137], s[18:19], v136, s1, v[6:7]
	v_mad_u64_u32 v[138:139], s[18:19], v138, s1, v[6:7]
	v_mad_u64_u32 v[140:141], s[18:19], v140, s1, v[6:7]
	v_mad_u64_u32 v[142:143], s[18:19], v142, s1, v[6:7]
	v_mad_u64_u32 v[144:145], s[18:19], v144, s1, v[6:7]
	s_lshl_b32 s17, s12, 1
	s_lshl_b32 s20, s13, 1
	v_or_b32_e32 v21, s17, v5
	v_or_b32_e32 v24, s20, v0
	s_add_i32 s21, s17, 4
	s_add_i32 s22, s20, 4
	s_add_i32 s23, s17, 8
	s_add_i32 s24, s20, 8
	s_add_i32 s25, s17, 12
	s_add_i32 s26, s20, 12
	s_add_i32 s27, s17, 16
	s_add_i32 s28, s20, 16
	s_add_i32 s29, s17, 20
	s_add_i32 s30, s20, 20
	s_add_i32 s31, s17, 24
	s_add_i32 s33, s20, 24
	s_add_i32 s35, s17, 28
	s_add_i32 s36, s20, 28
	v_mad_u64_u32 v[34:35], s[18:19], v24, s76, v[22:23]
	v_mad_u64_u32 v[36:37], s[18:19], v21, s76, v[22:23]
	v_or_b32_e32 v21, s21, v5
	v_or_b32_e32 v24, s22, v0
	v_or_b32_e32 v33, s23, v5
	v_or_b32_e32 v42, s24, v0
	v_or_b32_e32 v48, s25, v5
	v_or_b32_e32 v46, s26, v0
	v_or_b32_e32 v52, s27, v5
	v_or_b32_e32 v50, s28, v0
	v_or_b32_e32 v56, s29, v5
	v_or_b32_e32 v54, s30, v0
	v_or_b32_e32 v60, s31, v5
	v_or_b32_e32 v58, s33, v0
	v_or_b32_e32 v64, s35, v5
	v_or_b32_e32 v62, s36, v0
	v_mad_u64_u32 v[38:39], s[18:19], v24, s76, v[22:23]
	v_mad_u64_u32 v[40:41], s[18:19], v21, s76, v[22:23]
	v_mad_u64_u32 v[42:43], s[18:19], v42, s76, v[22:23]
	v_mad_u64_u32 v[44:45], s[18:19], v33, s76, v[22:23]
	v_mad_u64_u32 v[46:47], s[18:19], v46, s76, v[22:23]
	v_mad_u64_u32 v[48:49], s[18:19], v48, s76, v[22:23]
	v_mad_u64_u32 v[50:51], s[18:19], v50, s76, v[22:23]
	v_mad_u64_u32 v[52:53], s[18:19], v52, s76, v[22:23]
	v_mad_u64_u32 v[54:55], s[18:19], v54, s76, v[22:23]
	v_mad_u64_u32 v[56:57], s[18:19], v56, s76, v[22:23]
	v_mad_u64_u32 v[58:59], s[18:19], v58, s76, v[22:23]
	v_mad_u64_u32 v[60:61], s[18:19], v60, s76, v[22:23]
	v_mad_u64_u32 v[62:63], s[18:19], v62, s76, v[22:23]
	v_mad_u64_u32 v[64:65], s[18:19], v64, s76, v[22:23]
	global_load_dword v21, v[34:35], off
	global_load_dword v24, v[36:37], off
	global_load_dword v33, v[38:39], off
	global_load_dword v66, v[40:41], off
;     ...
; #pragma unroll 8
;     for (int i = 0; i < 32; ++i) { const int kk = 2 * i + (lane >> 5); scr[kk * 33 + (lane & 31)] = W[(size_t)(k0 + kk) * N + n0 + (lane & 31)]; }
	global_load_dword v67, v[42:43], off
	global_load_dword v68, v[44:45], off
	global_load_dword v69, v[46:47], off
	global_load_dword v70, v[48:49], off
	global_load_dword v71, v[50:51], off
	global_load_dword v72, v[52:53], off
	global_load_dword v73, v[54:55], off
	global_load_dword v74, v[56:57], off
	global_load_dword v75, v[58:59], off
	global_load_dword v76, v[60:61], off
	global_load_dword v77, v[62:63], off
	global_load_dword v78, v[64:65], off
	v_or_b32_e32 v36, s17, v3
	v_or_b32_e32 v34, s20, v2
	s_add_i32 s13, s13, 16
	s_add_i32 s12, s12, 16
	s_add_i32 s16, s16, -16
	v_mad_u64_u32 v[34:35], s[18:19], v34, s1, v[6:7]
	v_mad_u64_u32 v[36:37], s[18:19], v36, s1, v[6:7]
	v_or_b32_e32 v35, s21, v3
	v_or_b32_e32 v37, s22, v2
	v_or_b32_e32 v44, s23, v3
	v_or_b32_e32 v42, s24, v2
	v_or_b32_e32 v48, s25, v3
	v_or_b32_e32 v46, s26, v2
	v_or_b32_e32 v52, s27, v3
	v_or_b32_e32 v50, s28, v2
	v_or_b32_e32 v56, s29, v3
	v_or_b32_e32 v54, s30, v2
	v_or_b32_e32 v60, s31, v3
	v_or_b32_e32 v58, s33, v2
	v_or_b32_e32 v64, s35, v3
	v_or_b32_e32 v62, s36, v2
	s_cmp_lg_u32 s16, 0
	v_mad_u64_u32 v[38:39], s[18:19], v37, s1, v[6:7]
	v_mad_u64_u32 v[40:41], s[18:19], v35, s1, v[6:7]
	v_mad_u64_u32 v[42:43], s[18:19], v42, s1, v[6:7]
	v_mad_u64_u32 v[44:45], s[18:19], v44, s1, v[6:7]
	v_mad_u64_u32 v[46:47], s[18:19], v46, s1, v[6:7]
	v_mad_u64_u32 v[48:49], s[18:19], v48, s1, v[6:7]
	v_mad_u64_u32 v[50:51], s[18:19], v50, s1, v[6:7]
	v_mad_u64_u32 v[52:53], s[18:19], v52, s1, v[6:7]
	v_mad_u64_u32 v[54:55], s[18:19], v54, s1, v[6:7]
	v_mad_u64_u32 v[56:57], s[18:19], v56, s1, v[6:7]
	v_mad_u64_u32 v[58:59], s[18:19], v58, s1, v[6:7]
	v_mad_u64_u32 v[60:61], s[18:19], v60, s1, v[6:7]
	v_mad_u64_u32 v[62:63], s[18:19], v62, s1, v[6:7]
	v_mad_u64_u32 v[64:65], s[18:19], v64, s1, v[6:7]
	s_waitcnt vmcnt(31)
	ds_write_b32 v114, v101
	s_waitcnt vmcnt(30)
	ds_write_b32 v116, v104
	s_waitcnt vmcnt(29)
	ds_write_b32 v118, v113
	s_waitcnt vmcnt(28)
	ds_write_b32 v120, v146
	s_waitcnt vmcnt(27)
	ds_write_b32 v122, v147
	s_waitcnt vmcnt(26)
	ds_write_b32 v124, v148
	s_waitcnt vmcnt(25)
	ds_write_b32 v126, v149
	s_waitcnt vmcnt(24)
	ds_write_b32 v128, v150
	s_waitcnt vmcnt(23)
	ds_write_b32 v130, v151
	s_waitcnt vmcnt(22)
	ds_write_b32 v132, v152
	s_waitcnt vmcnt(21)
	ds_write_b32 v134, v153
	s_waitcnt vmcnt(20)
	ds_write_b32 v136, v154
	s_waitcnt vmcnt(19)
	ds_write_b32 v138, v155
	s_waitcnt vmcnt(18)
	ds_write_b32 v140, v156
	s_waitcnt vmcnt(17)
	ds_write_b32 v142, v157
	s_waitcnt vmcnt(16)
	ds_write_b32 v144, v158
	s_waitcnt vmcnt(15)
	ds_write_b32 v34, v21
	s_waitcnt vmcnt(14)
	ds_write_b32 v36, v24
	s_waitcnt vmcnt(13)
	ds_write_b32 v38, v33
	s_waitcnt vmcnt(12)
	ds_write_b32 v40, v66
	s_waitcnt vmcnt(11)
	ds_write_b32 v42, v67
	s_waitcnt vmcnt(10)
	ds_write_b32 v44, v68
	s_waitcnt vmcnt(9)
	ds_write_b32 v46, v69
	s_waitcnt vmcnt(8)
	ds_write_b32 v48, v70
	s_waitcnt vmcnt(7)
	ds_write_b32 v50, v71
	s_waitcnt vmcnt(6)
	ds_write_b32 v52, v72
	s_waitcnt vmcnt(5)
	ds_write_b32 v54, v73
	s_waitcnt vmcnt(4)
	ds_write_b32 v56, v74
	s_waitcnt vmcnt(3)
	ds_write_b32 v58, v75
	s_waitcnt vmcnt(2)
	ds_write_b32 v60, v76
	s_waitcnt vmcnt(1)
	ds_write_b32 v62, v77
	s_waitcnt vmcnt(0)
	ds_write_b32 v64, v78
	s_waitcnt lgkmcnt(0)
	ds_read2_b32 v[22:23], v25 offset1:8
	ds_read2_b32 v[40:41], v25 offset0:33 offset1:41
	ds_read2_b32 v[42:43], v25 offset0:66 offset1:74
	ds_read2_b32 v[44:45], v25 offset0:99 offset1:107
	ds_read2_b32 v[46:47], v25 offset0:132 offset1:140
	s_waitcnt lgkmcnt(4)
	v_bfe_u32 v0, v22, 16, 1
	v_add3_u32 v0, v22, v0, s85
	s_waitcnt lgkmcnt(3)
	v_bfe_u32 v5, v40, 16, 1
	v_lshrrev_b32_e32 v0, 16, v0
	v_add3_u32 v5, v40, v5, s85
	ds_read2_b32 v[48:49], v25 offset0:165 offset1:173
	v_and_or_b32 v34, v5, s3, v0
	s_waitcnt lgkmcnt(3)
	v_bfe_u32 v0, v42, 16, 1
	v_add3_u32 v0, v42, v0, s85
	s_waitcnt lgkmcnt(2)
; #define GAS __attribute__((address_space(1)))
; #define LAS __attribute__((address_space(3)))
; #define LDS_WAIT() asm volatile("s_waitcnt lgkmcnt(0)" ::: "memory")
; __device__ __forceinline__ unsigned pk2(float lo, float hi) { return f2bf(lo) | (f2bf(hi) << 16); }
;     ...
;     const int c = lane & 7;
; #pragma unroll
;     for (int j = 0; j < 4; ++j) { const int n = (lane >> 3) + 8 * j; const LAS float* s = scr + (8 * c) * 33 + n;
;         v4u o; o.x = pk2(s[0 * 33], s[1 * 33]); o.y = pk2(s[2 * 33], s[3 * 33]); o.z = pk2(s[4 * 33], s[5 * 33]); o.w = pk2(s[6 * 33], s[7 * 33]);
;         const int nr = pg ? (8 * ((n >> 2) & 3) + 4 * (n >> 4) + (n & 3)) : n;
;         *(GAS v4u*)(WT + (size_t)(n0 + nr) * K + k0 + 8 * c) = o; }
;     LDS_WAIT(); asm volatile("" ::: "memory");
	v_bfe_u32 v5, v44, 16, 1
	ds_read2_b32 v[50:51], v25 offset0:198 offset1:206
	v_lshrrev_b32_e32 v0, 16, v0
	v_add3_u32 v5, v44, v5, s85
	ds_read2_b32 v[52:53], v25 offset0:231 offset1:239
	v_and_or_b32 v35, v5, s3, v0
	s_waitcnt lgkmcnt(3)
	v_bfe_u32 v0, v46, 16, 1
	v_add3_u32 v0, v46, v0, s85
	s_waitcnt lgkmcnt(2)
	v_bfe_u32 v5, v48, 16, 1
	v_lshrrev_b32_e32 v0, 16, v0
	v_add3_u32 v5, v48, v5, s85
	v_and_or_b32 v36, v5, s3, v0
	s_waitcnt lgkmcnt(1)
	v_bfe_u32 v0, v50, 16, 1
	v_add3_u32 v0, v50, v0, s85
	s_waitcnt lgkmcnt(0)
	v_bfe_u32 v5, v52, 16, 1
	s_and_b32 s11, 0xffff, s11
	s_and_b32 s10, 0xffff, s10
	v_lshrrev_b32_e32 v0, 16, v0
	v_add3_u32 v5, v52, v5, s85
	s_lshl_b32 s78, s10, 1
	v_and_or_b32 v37, v5, s3, v0
	v_or_b32_e32 v0, s11, v7
	v_lshl_add_u64 v[38:39], v[12:13], 0, s[78:79]
	v_lshlrev_b32_e32 v0, 12, v0
	v_lshl_add_u64 v[54:55], v[38:39], 0, v[0:1]
	v_bfe_u32 v0, v23, 16, 1
	v_add3_u32 v0, v23, v0, s85
	v_bfe_u32 v5, v41, 16, 1
	v_lshrrev_b32_e32 v0, 16, v0
	v_add3_u32 v5, v41, v5, s85
	global_store_dwordx4 v[54:55], v[34:37], off
	ds_read2_b32 v[22:23], v25 offset0:16 offset1:24
	s_nop 0
	v_and_or_b32 v34, v5, s3, v0
	v_bfe_u32 v0, v43, 16, 1
	v_add3_u32 v0, v43, v0, s85
	v_bfe_u32 v5, v45, 16, 1
	v_lshrrev_b32_e32 v0, 16, v0
	v_add3_u32 v5, v45, v5, s85
	v_and_or_b32 v35, v5, s3, v0
	v_bfe_u32 v0, v47, 16, 1
	v_add3_u32 v0, v47, v0, s85
	v_bfe_u32 v5, v49, 16, 1
	v_lshrrev_b32_e32 v0, 16, v0
	v_add3_u32 v5, v49, v5, s85
	v_and_or_b32 v36, v5, s3, v0
	v_bfe_u32 v0, v51, 16, 1
	v_add3_u32 v0, v51, v0, s85
	v_bfe_u32 v5, v53, 16, 1
	v_lshrrev_b32_e32 v0, 16, v0
	v_add3_u32 v5, v53, v5, s85
	v_and_or_b32 v37, v5, s3, v0
	v_or_b32_e32 v0, s11, v26
	v_lshlrev_b32_e32 v0, 12, v0
	v_lshl_add_u64 v[40:41], v[38:39], 0, v[0:1]
	global_store_dwordx4 v[40:41], v[34:37], off
	ds_read2_b32 v[40:41], v25 offset0:49 offset1:57
	ds_read2_b32 v[42:43], v25 offset0:82 offset1:90
	ds_read2_b32 v[44:45], v25 offset0:115 offset1:123
	s_waitcnt lgkmcnt(3)
	v_bfe_u32 v0, v22, 16, 1
	v_add3_u32 v0, v22, v0, s85
	s_waitcnt lgkmcnt(2)
	v_bfe_u32 v5, v40, 16, 1
	ds_read2_b32 v[46:47], v25 offset0:148 offset1:156
	v_lshrrev_b32_e32 v0, 16, v0
	v_add3_u32 v5, v40, v5, s85
	ds_read2_b32 v[48:49], v25 offset0:181 offset1:189
	v_and_or_b32 v34, v5, s3, v0
	s_waitcnt lgkmcnt(3)
	v_bfe_u32 v0, v42, 16, 1
	v_add3_u32 v0, v42, v0, s85
	s_waitcnt lgkmcnt(2)
	v_bfe_u32 v5, v44, 16, 1
	ds_read2_b32 v[50:51], v25 offset0:214 offset1:222
	v_lshrrev_b32_e32 v0, 16, v0
	v_add3_u32 v5, v44, v5, s85
	ds_read2_b32 v[52:53], v25 offset0:247 offset1:255
	v_and_or_b32 v35, v5, s3, v0
	s_waitcnt lgkmcnt(3)
	v_bfe_u32 v0, v46, 16, 1
	v_add3_u32 v0, v46, v0, s85
	s_waitcnt lgkmcnt(2)
	v_bfe_u32 v5, v48, 16, 1
	v_lshrrev_b32_e32 v0, 16, v0
	v_add3_u32 v5, v48, v5, s85
	v_and_or_b32 v36, v5, s3, v0
	s_waitcnt lgkmcnt(1)
	v_bfe_u32 v0, v50, 16, 1
	v_add3_u32 v0, v50, v0, s85
	s_waitcnt lgkmcnt(0)
	v_bfe_u32 v5, v52, 16, 1
	v_lshrrev_b32_e32 v0, 16, v0
	v_add3_u32 v5, v52, v5, s85
	v_and_or_b32 v37, v5, s3, v0
	v_or_b32_e32 v0, s11, v27
	v_lshlrev_b32_e32 v0, 12, v0
	v_lshl_add_u64 v[54:55], v[38:39], 0, v[0:1]
	v_bfe_u32 v0, v23, 16, 1
	v_add3_u32 v0, v23, v0, s85
	v_bfe_u32 v5, v41, 16, 1
	v_lshrrev_b32_e32 v0, 16, v0
	v_add3_u32 v5, v41, v5, s85
	global_store_dwordx4 v[54:55], v[34:37], off
	s_nop 1
	v_and_or_b32 v34, v5, s3, v0
	v_bfe_u32 v0, v43, 16, 1
	v_add3_u32 v0, v43, v0, s85
	v_bfe_u32 v5, v45, 16, 1
	v_lshrrev_b32_e32 v0, 16, v0
	v_add3_u32 v5, v45, v5, s85
	v_and_or_b32 v35, v5, s3, v0
	v_bfe_u32 v0, v47, 16, 1
	v_add3_u32 v0, v47, v0, s85
	v_bfe_u32 v5, v49, 16, 1
	v_lshrrev_b32_e32 v0, 16, v0
	v_add3_u32 v5, v49, v5, s85
	v_and_or_b32 v36, v5, s3, v0
	v_bfe_u32 v0, v51, 16, 1
	v_add3_u32 v0, v51, v0, s85
	v_bfe_u32 v5, v53, 16, 1
	v_lshrrev_b32_e32 v0, 16, v0
	v_add3_u32 v5, v53, v5, s85
	v_and_or_b32 v37, v5, s3, v0
	v_or_b32_e32 v0, s11, v28
	v_lshlrev_b32_e32 v0, 12, v0
	v_lshl_add_u64 v[22:23], v[38:39], 0, v[0:1]
	global_store_dwordx4 v[22:23], v[34:37], off
	s_waitcnt lgkmcnt(0)

;     ...
; #pragma unroll 8
;     for (int i = 0; i < 32; ++i) { const int kk = 2 * i + (lane >> 5); scr[kk * 33 + (lane & 31)] = W[(size_t)(k0 + kk) * N + n0 + (lane & 31)]; }
.LBB0_430:
	s_lshl_b32 s17, s12, 1
	s_lshl_b32 s20, s13, 1
	v_or_b32_e32 v101, s17, v5
	v_or_b32_e32 v104, s20, v0
	s_add_i32 s21, s17, 4
	s_add_i32 s22, s20, 4
	s_add_i32 s23, s17, 8
	s_add_i32 s24, s20, 8
	s_add_i32 s25, s17, 12
	s_add_i32 s26, s20, 12
	s_add_i32 s27, s17, 16
	s_add_i32 s28, s20, 16
	s_add_i32 s29, s17, 20
	s_add_i32 s30, s20, 20
	s_add_i32 s31, s17, 24
	s_add_i32 s33, s20, 24
	s_add_i32 s35, s17, 28
	s_add_i32 s36, s20, 28
	v_mad_u64_u32 v[114:115], s[18:19], v104, s77, v[22:23]
	v_mad_u64_u32 v[116:117], s[18:19], v101, s77, v[22:23]
	v_or_b32_e32 v101, s21, v5
	v_or_b32_e32 v104, s22, v0
	v_or_b32_e32 v113, s23, v5
	v_or_b32_e32 v122, s24, v0
	v_or_b32_e32 v128, s25, v5
	v_or_b32_e32 v126, s26, v0
	v_or_b32_e32 v132, s27, v5
	v_or_b32_e32 v130, s28, v0
	v_or_b32_e32 v136, s29, v5
	v_or_b32_e32 v134, s30, v0
	v_or_b32_e32 v140, s31, v5
	v_or_b32_e32 v138, s33, v0
	v_or_b32_e32 v144, s35, v5
	v_or_b32_e32 v142, s36, v0
	v_mad_u64_u32 v[118:119], s[18:19], v104, s77, v[22:23]
	v_mad_u64_u32 v[120:121], s[18:19], v101, s77, v[22:23]
	v_mad_u64_u32 v[122:123], s[18:19], v122, s77, v[22:23]
	v_mad_u64_u32 v[124:125], s[18:19], v113, s77, v[22:23]
	v_mad_u64_u32 v[126:127], s[18:19], v126, s77, v[22:23]
	v_mad_u64_u32 v[128:129], s[18:19], v128, s77, v[22:23]
	v_mad_u64_u32 v[130:131], s[18:19], v130, s77, v[22:23]
	v_mad_u64_u32 v[132:133], s[18:19], v132, s77, v[22:23]
	v_mad_u64_u32 v[134:135], s[18:19], v134, s77, v[22:23]
	v_mad_u64_u32 v[136:137], s[18:19], v136, s77, v[22:23]
	v_mad_u64_u32 v[138:139], s[18:19], v138, s77, v[22:23]
	v_mad_u64_u32 v[140:141], s[18:19], v140, s77, v[22:23]
	v_mad_u64_u32 v[142:143], s[18:19], v142, s77, v[22:23]
	v_mad_u64_u32 v[144:145], s[18:19], v144, s77, v[22:23]
	global_load_dword v101, v[114:115], off
	global_load_dword v104, v[116:117], off
	global_load_dword v113, v[118:119], off
	global_load_dword v146, v[120:121], off
	global_load_dword v147, v[122:123], off
	global_load_dword v148, v[124:125], off
	global_load_dword v149, v[126:127], off
	global_load_dword v150, v[128:129], off
	global_load_dword v151, v[130:131], off
	global_load_dword v152, v[132:133], off
	global_load_dword v153, v[134:135], off
	global_load_dword v154, v[136:137], off
	global_load_dword v155, v[138:139], off
	global_load_dword v156, v[140:141], off
	global_load_dword v157, v[142:143], off
	global_load_dword v158, v[144:145], off
	v_or_b32_e32 v116, s17, v3
	v_or_b32_e32 v114, s20, v2
	s_add_i32 s13, s13, 16
	s_add_i32 s12, s12, 16
	s_add_i32 s16, s16, -16
	v_mad_u64_u32 v[114:115], s[18:19], v114, s1, v[6:7]
	v_mad_u64_u32 v[116:117], s[18:19], v116, s1, v[6:7]
	v_or_b32_e32 v115, s21, v3
	v_or_b32_e32 v117, s22, v2
	v_or_b32_e32 v124, s23, v3
	v_or_b32_e32 v122, s24, v2
	v_or_b32_e32 v128, s25, v3
	v_or_b32_e32 v126, s26, v2
	v_or_b32_e32 v132, s27, v3
	v_or_b32_e32 v130, s28, v2
	v_or_b32_e32 v136, s29, v3
	v_or_b32_e32 v134, s30, v2
	v_or_b32_e32 v140, s31, v3
	v_or_b32_e32 v138, s33, v2
	v_or_b32_e32 v144, s35, v3
	v_or_b32_e32 v142, s36, v2
	s_cmp_lg_u32 s16, 0
	v_mad_u64_u32 v[118:119], s[18:19], v117, s1, v[6:7]
	v_mad_u64_u32 v[120:121], s[18:19], v115, s1, v[6:7]
	v_mad_u64_u32 v[122:123], s[18:19], v122, s1, v[6:7]
	v_mad_u64_u32 v[124:125], s[18:19], v124, s1, v[6:7]
	v_mad_u64_u32 v[126:127], s[18:19], v126, s1, v[6:7]
	v_mad_u64_u32 v[128:129], s[18:19], v128, s1, v[6:7]
	v_mad_u64_u32 v[130:131], s[18:19], v130, s1, v[6:7]
	v_mad_u64_u32 v[132:133], s[18:19], v132, s1, v[6:7]
	v_mad_u64_u32 v[134:135], s[18:19], v134, s1, v[6:7]
	v_mad_u64_u32 v[136:137], s[18:19], v136, s1, v[6:7]
	v_mad_u64_u32 v[138:139], s[18:19], v138, s1, v[6:7]
	v_mad_u64_u32 v[140:141], s[18:19], v140, s1, v[6:7]
	v_mad_u64_u32 v[142:143], s[18:19], v142, s1, v[6:7]
	v_mad_u64_u32 v[144:145], s[18:19], v144, s1, v[6:7]
	s_lshl_b32 s17, s12, 1
	s_lshl_b32 s20, s13, 1
	v_or_b32_e32 v21, s17, v5
	v_or_b32_e32 v24, s20, v0
	s_add_i32 s21, s17, 4
	s_add_i32 s22, s20, 4
	s_add_i32 s23, s17, 8
	s_add_i32 s24, s20, 8
	s_add_i32 s25, s17, 12
	s_add_i32 s26, s20, 12
	s_add_i32 s27, s17, 16
	s_add_i32 s28, s20, 16
	s_add_i32 s29, s17, 20
	s_add_i32 s30, s20, 20
	s_add_i32 s31, s17, 24
	s_add_i32 s33, s20, 24
	s_add_i32 s35, s17, 28
	s_add_i32 s36, s20, 28
	v_mad_u64_u32 v[34:35], s[18:19], v24, s77, v[22:23]
	v_mad_u64_u32 v[36:37], s[18:19], v21, s77, v[22:23]
	v_or_b32_e32 v21, s21, v5
	v_or_b32_e32 v24, s22, v0
	v_or_b32_e32 v33, s23, v5
	v_or_b32_e32 v42, s24, v0
	v_or_b32_e32 v48, s25, v5
	v_or_b32_e32 v46, s26, v0
	v_or_b32_e32 v52, s27, v5
	v_or_b32_e32 v50, s28, v0
	v_or_b32_e32 v56, s29, v5
	v_or_b32_e32 v54, s30, v0
	v_or_b32_e32 v60, s31, v5
	v_or_b32_e32 v58, s33, v0
	v_or_b32_e32 v64, s35, v5
	v_or_b32_e32 v62, s36, v0
	v_mad_u64_u32 v[38:39], s[18:19], v24, s77, v[22:23]
	v_mad_u64_u32 v[40:41], s[18:19], v21, s77, v[22:23]
	v_mad_u64_u32 v[42:43], s[18:19], v42, s77, v[22:23]
	v_mad_u64_u32 v[44:45], s[18:19], v33, s77, v[22:23]
	v_mad_u64_u32 v[46:47], s[18:19], v46, s77, v[22:23]
	v_mad_u64_u32 v[48:49], s[18:19], v48, s77, v[22:23]
	v_mad_u64_u32 v[50:51], s[18:19], v50, s77, v[22:23]
	v_mad_u64_u32 v[52:53], s[18:19], v52, s77, v[22:23]
	v_mad_u64_u32 v[54:55], s[18:19], v54, s77, v[22:23]
	v_mad_u64_u32 v[56:57], s[18:19], v56, s77, v[22:23]
	v_mad_u64_u32 v[58:59], s[18:19], v58, s77, v[22:23]
	v_mad_u64_u32 v[60:61], s[18:19], v60, s77, v[22:23]
	v_mad_u64_u32 v[62:63], s[18:19], v62, s77, v[22:23]
	v_mad_u64_u32 v[64:65], s[18:19], v64, s77, v[22:23]
	global_load_dword v21, v[34:35], off
	global_load_dword v24, v[36:37], off
	global_load_dword v33, v[38:39], off
	global_load_dword v66, v[40:41], off
;     ...
; #pragma unroll 8
;     for (int i = 0; i < 32; ++i) { const int kk = 2 * i + (lane >> 5); scr[kk * 33 + (lane & 31)] = W[(size_t)(k0 + kk) * N + n0 + (lane & 31)]; }
	global_load_dword v67, v[42:43], off
	global_load_dword v68, v[44:45], off
	global_load_dword v69, v[46:47], off
	global_load_dword v70, v[48:49], off
	global_load_dword v71, v[50:51], off
	global_load_dword v72, v[52:53], off
	global_load_dword v73, v[54:55], off
	global_load_dword v74, v[56:57], off
	global_load_dword v75, v[58:59], off
	global_load_dword v76, v[60:61], off
	global_load_dword v77, v[62:63], off
	global_load_dword v78, v[64:65], off
	v_or_b32_e32 v36, s17, v3
	v_or_b32_e32 v34, s20, v2
	s_add_i32 s13, s13, 16
	s_add_i32 s12, s12, 16
	s_add_i32 s16, s16, -16
	v_mad_u64_u32 v[34:35], s[18:19], v34, s1, v[6:7]
	v_mad_u64_u32 v[36:37], s[18:19], v36, s1, v[6:7]
	v_or_b32_e32 v35, s21, v3
	v_or_b32_e32 v37, s22, v2
	v_or_b32_e32 v44, s23, v3
	v_or_b32_e32 v42, s24, v2
	v_or_b32_e32 v48, s25, v3
	v_or_b32_e32 v46, s26, v2
	v_or_b32_e32 v52, s27, v3
	v_or_b32_e32 v50, s28, v2
	v_or_b32_e32 v56, s29, v3
	v_or_b32_e32 v54, s30, v2
	v_or_b32_e32 v60, s31, v3
	v_or_b32_e32 v58, s33, v2
	v_or_b32_e32 v64, s35, v3
	v_or_b32_e32 v62, s36, v2
	s_cmp_lg_u32 s16, 0
	v_mad_u64_u32 v[38:39], s[18:19], v37, s1, v[6:7]
	v_mad_u64_u32 v[40:41], s[18:19], v35, s1, v[6:7]
	v_mad_u64_u32 v[42:43], s[18:19], v42, s1, v[6:7]
	v_mad_u64_u32 v[44:45], s[18:19], v44, s1, v[6:7]
	v_mad_u64_u32 v[46:47], s[18:19], v46, s1, v[6:7]
	v_mad_u64_u32 v[48:49], s[18:19], v48, s1, v[6:7]
	v_mad_u64_u32 v[50:51], s[18:19], v50, s1, v[6:7]
	v_mad_u64_u32 v[52:53], s[18:19], v52, s1, v[6:7]
	v_mad_u64_u32 v[54:55], s[18:19], v54, s1, v[6:7]
	v_mad_u64_u32 v[56:57], s[18:19], v56, s1, v[6:7]
	v_mad_u64_u32 v[58:59], s[18:19], v58, s1, v[6:7]
	v_mad_u64_u32 v[60:61], s[18:19], v60, s1, v[6:7]
	v_mad_u64_u32 v[62:63], s[18:19], v62, s1, v[6:7]
	v_mad_u64_u32 v[64:65], s[18:19], v64, s1, v[6:7]
	s_waitcnt vmcnt(31)
	ds_write_b32 v114, v101
	s_waitcnt vmcnt(30)
	ds_write_b32 v116, v104
	s_waitcnt vmcnt(29)
	ds_write_b32 v118, v113
	s_waitcnt vmcnt(28)
	ds_write_b32 v120, v146
	s_waitcnt vmcnt(27)
	ds_write_b32 v122, v147
	s_waitcnt vmcnt(26)
	ds_write_b32 v124, v148
	s_waitcnt vmcnt(25)
	ds_write_b32 v126, v149
	s_waitcnt vmcnt(24)
	ds_write_b32 v128, v150
	s_waitcnt vmcnt(23)
	ds_write_b32 v130, v151
	s_waitcnt vmcnt(22)
	ds_write_b32 v132, v152
	s_waitcnt vmcnt(21)
	ds_write_b32 v134, v153
	s_waitcnt vmcnt(20)
	ds_write_b32 v136, v154
	s_waitcnt vmcnt(19)
	ds_write_b32 v138, v155
	s_waitcnt vmcnt(18)
	ds_write_b32 v140, v156
	s_waitcnt vmcnt(17)
	ds_write_b32 v142, v157
	s_waitcnt vmcnt(16)
	ds_write_b32 v144, v158
	s_waitcnt vmcnt(15)
	ds_write_b32 v34, v21
	s_waitcnt vmcnt(14)
	ds_write_b32 v36, v24
	s_waitcnt vmcnt(13)
	ds_write_b32 v38, v33
	s_waitcnt vmcnt(12)
	ds_write_b32 v40, v66
	s_waitcnt vmcnt(11)
	ds_write_b32 v42, v67
	s_waitcnt vmcnt(10)
	ds_write_b32 v44, v68
	s_waitcnt vmcnt(9)
	ds_write_b32 v46, v69
	s_waitcnt vmcnt(8)
	ds_write_b32 v48, v70
	s_waitcnt vmcnt(7)
	ds_write_b32 v50, v71
	s_waitcnt vmcnt(6)
	ds_write_b32 v52, v72
	s_waitcnt vmcnt(5)
	ds_write_b32 v54, v73
	s_waitcnt vmcnt(4)
	ds_write_b32 v56, v74
	s_waitcnt vmcnt(3)
	ds_write_b32 v58, v75
	s_waitcnt vmcnt(2)
	ds_write_b32 v60, v76
	s_waitcnt vmcnt(1)
	ds_write_b32 v62, v77
	s_waitcnt vmcnt(0)
	ds_write_b32 v64, v78
	s_waitcnt lgkmcnt(0)
	ds_read2_b32 v[22:23], v25 offset1:8
	ds_read2_b32 v[40:41], v25 offset0:33 offset1:41
	ds_read2_b32 v[42:43], v25 offset0:66 offset1:74
	ds_read2_b32 v[44:45], v25 offset0:99 offset1:107
	ds_read2_b32 v[46:47], v25 offset0:132 offset1:140
	s_waitcnt lgkmcnt(4)
	v_bfe_u32 v0, v22, 16, 1
	v_add3_u32 v0, v22, v0, s85
	s_waitcnt lgkmcnt(3)
	v_bfe_u32 v5, v40, 16, 1
	v_lshrrev_b32_e32 v0, 16, v0
	v_add3_u32 v5, v40, v5, s85
	ds_read2_b32 v[48:49], v25 offset0:165 offset1:173
	v_and_or_b32 v34, v5, s3, v0
	s_waitcnt lgkmcnt(3)
	v_bfe_u32 v0, v42, 16, 1
	v_add3_u32 v0, v42, v0, s85
	s_waitcnt lgkmcnt(2)
; #define GAS __attribute__((address_space(1)))
; #define LAS __attribute__((address_space(3)))
; #define LDS_WAIT() asm volatile("s_waitcnt lgkmcnt(0)" ::: "memory")
; __device__ __forceinline__ unsigned pk2(float lo, float hi) { return f2bf(lo) | (f2bf(hi) << 16); }
;     ...
;     const int c = lane & 7;
; #pragma unroll
;     for (int j = 0; j < 4; ++j) { const int n = (lane >> 3) + 8 * j; const LAS float* s = scr + (8 * c) * 33 + n;
;         v4u o; o.x = pk2(s[0 * 33], s[1 * 33]); o.y = pk2(s[2 * 33], s[3 * 33]); o.z = pk2(s[4 * 33], s[5 * 33]); o.w = pk2(s[6 * 33], s[7 * 33]);
;         const int nr = pg ? (8 * ((n >> 2) & 3) + 4 * (n >> 4) + (n & 3)) : n;
;         *(GAS v4u*)(WT + (size_t)(n0 + nr) * K + k0 + 8 * c) = o; }
;     LDS_WAIT(); asm volatile("" ::: "memory");
	v_bfe_u32 v5, v44, 16, 1
	ds_read2_b32 v[50:51], v25 offset0:198 offset1:206
	v_lshrrev_b32_e32 v0, 16, v0
	v_add3_u32 v5, v44, v5, s85
	ds_read2_b32 v[52:53], v25 offset0:231 offset1:239
	v_and_or_b32 v35, v5, s3, v0
	s_waitcnt lgkmcnt(3)
	v_bfe_u32 v0, v46, 16, 1
	v_add3_u32 v0, v46, v0, s85
	s_waitcnt lgkmcnt(2)
	v_bfe_u32 v5, v48, 16, 1
	v_lshrrev_b32_e32 v0, 16, v0
	v_add3_u32 v5, v48, v5, s85
	v_and_or_b32 v36, v5, s3, v0
	s_waitcnt lgkmcnt(1)
	v_bfe_u32 v0, v50, 16, 1
	v_add3_u32 v0, v50, v0, s85
	s_waitcnt lgkmcnt(0)
	v_bfe_u32 v5, v52, 16, 1
	s_and_b32 s11, 0xffff, s11
	s_and_b32 s10, 0xffff, s10
	v_lshrrev_b32_e32 v0, 16, v0
	v_add3_u32 v5, v52, v5, s85
	s_lshl_b32 s78, s10, 1
	v_and_or_b32 v37, v5, s3, v0
	v_or_b32_e32 v0, s11, v7
	v_lshl_add_u64 v[38:39], v[14:15], 0, s[78:79]
	v_lshlrev_b32_e32 v0, 12, v0
	v_lshl_add_u64 v[54:55], v[38:39], 0, v[0:1]
	v_bfe_u32 v0, v23, 16, 1
	v_add3_u32 v0, v23, v0, s85
	v_bfe_u32 v5, v41, 16, 1
	v_lshrrev_b32_e32 v0, 16, v0
	v_add3_u32 v5, v41, v5, s85
	global_store_dwordx4 v[54:55], v[34:37], off
	ds_read2_b32 v[22:23], v25 offset0:16 offset1:24
	s_nop 0
	v_and_or_b32 v34, v5, s3, v0
	v_bfe_u32 v0, v43, 16, 1
	v_add3_u32 v0, v43, v0, s85
	v_bfe_u32 v5, v45, 16, 1
	v_lshrrev_b32_e32 v0, 16, v0
	v_add3_u32 v5, v45, v5, s85
	v_and_or_b32 v35, v5, s3, v0
	v_bfe_u32 v0, v47, 16, 1
	v_add3_u32 v0, v47, v0, s85
	v_bfe_u32 v5, v49, 16, 1
	v_lshrrev_b32_e32 v0, 16, v0
	v_add3_u32 v5, v49, v5, s85
	v_and_or_b32 v36, v5, s3, v0
	v_bfe_u32 v0, v51, 16, 1
	v_add3_u32 v0, v51, v0, s85
	v_bfe_u32 v5, v53, 16, 1
	v_lshrrev_b32_e32 v0, 16, v0
	v_add3_u32 v5, v53, v5, s85
	v_and_or_b32 v37, v5, s3, v0
	v_or_b32_e32 v0, s11, v26
	v_lshlrev_b32_e32 v0, 12, v0
	v_lshl_add_u64 v[40:41], v[38:39], 0, v[0:1]
	global_store_dwordx4 v[40:41], v[34:37], off
	ds_read2_b32 v[40:41], v25 offset0:49 offset1:57
	ds_read2_b32 v[42:43], v25 offset0:82 offset1:90
	ds_read2_b32 v[44:45], v25 offset0:115 offset1:123
	s_waitcnt lgkmcnt(3)
	v_bfe_u32 v0, v22, 16, 1
	v_add3_u32 v0, v22, v0, s85
	s_waitcnt lgkmcnt(2)
	v_bfe_u32 v5, v40, 16, 1
	ds_read2_b32 v[46:47], v25 offset0:148 offset1:156
	v_lshrrev_b32_e32 v0, 16, v0
	v_add3_u32 v5, v40, v5, s85
	ds_read2_b32 v[48:49], v25 offset0:181 offset1:189
	v_and_or_b32 v34, v5, s3, v0
	s_waitcnt lgkmcnt(3)
	v_bfe_u32 v0, v42, 16, 1
	v_add3_u32 v0, v42, v0, s85
	s_waitcnt lgkmcnt(2)
	v_bfe_u32 v5, v44, 16, 1
	ds_read2_b32 v[50:51], v25 offset0:214 offset1:222
	v_lshrrev_b32_e32 v0, 16, v0
	v_add3_u32 v5, v44, v5, s85
	ds_read2_b32 v[52:53], v25 offset0:247 offset1:255
	v_and_or_b32 v35, v5, s3, v0
	s_waitcnt lgkmcnt(3)
	v_bfe_u32 v0, v46, 16, 1
	v_add3_u32 v0, v46, v0, s85
	s_waitcnt lgkmcnt(2)
	v_bfe_u32 v5, v48, 16, 1
	v_lshrrev_b32_e32 v0, 16, v0
	v_add3_u32 v5, v48, v5, s85
	v_and_or_b32 v36, v5, s3, v0
	s_waitcnt lgkmcnt(1)
	v_bfe_u32 v0, v50, 16, 1
	v_add3_u32 v0, v50, v0, s85
	s_waitcnt lgkmcnt(0)
	v_bfe_u32 v5, v52, 16, 1
	v_lshrrev_b32_e32 v0, 16, v0
	v_add3_u32 v5, v52, v5, s85
	v_and_or_b32 v37, v5, s3, v0
	v_or_b32_e32 v0, s11, v27
	v_lshlrev_b32_e32 v0, 12, v0
	v_lshl_add_u64 v[54:55], v[38:39], 0, v[0:1]
	v_bfe_u32 v0, v23, 16, 1
	v_add3_u32 v0, v23, v0, s85
	v_bfe_u32 v5, v41, 16, 1
	v_lshrrev_b32_e32 v0, 16, v0
	v_add3_u32 v5, v41, v5, s85
	global_store_dwordx4 v[54:55], v[34:37], off
	s_nop 1
	v_and_or_b32 v34, v5, s3, v0
	v_bfe_u32 v0, v43, 16, 1
	v_add3_u32 v0, v43, v0, s85
	v_bfe_u32 v5, v45, 16, 1
	v_lshrrev_b32_e32 v0, 16, v0
	v_add3_u32 v5, v45, v5, s85
	v_and_or_b32 v35, v5, s3, v0
	v_bfe_u32 v0, v47, 16, 1
	v_add3_u32 v0, v47, v0, s85
	v_bfe_u32 v5, v49, 16, 1
	v_lshrrev_b32_e32 v0, 16, v0
	v_add3_u32 v5, v49, v5, s85
	v_and_or_b32 v36, v5, s3, v0
	v_bfe_u32 v0, v51, 16, 1
	v_add3_u32 v0, v51, v0, s85
	v_bfe_u32 v5, v53, 16, 1
	v_lshrrev_b32_e32 v0, 16, v0
	v_add3_u32 v5, v53, v5, s85
	v_and_or_b32 v37, v5, s3, v0
	v_or_b32_e32 v0, s11, v28
	v_lshlrev_b32_e32 v0, 12, v0
	v_lshl_add_u64 v[22:23], v[38:39], 0, v[0:1]
	global_store_dwordx4 v[22:23], v[34:37], off
	s_waitcnt lgkmcnt(0)

;     ...
; #pragma unroll 8
;     for (int i = 0; i < 32; ++i) { const int kk = 2 * i + (lane >> 5); scr[kk * 33 + (lane & 31)] = W[(size_t)(k0 + kk) * N + n0 + (lane & 31)]; }
.LBB0_435:
	v_mov_b32_e32 v81, v1
	s_lshl_b32 s18, s13, 1
	s_lshl_b32 s19, s16, 1
	v_or_b32_e32 v80, s19, v24
	s_add_i32 s20, s18, 4
	s_add_i32 s21, s19, 4
	v_mov_b32_e32 v117, v1
	s_add_i32 s23, s19, 8
	v_lshlrev_b64 v[130:131], 15, v[80:81]
	v_or_b32_e32 v116, s20, v5
	v_or_b32_e32 v80, s21, v24
	v_mov_b32_e32 v115, v1
	v_or_b32_e32 v114, s18, v5
	s_add_i32 s25, s19, 12
	v_lshlrev_b64 v[116:117], 15, v[116:117]
	v_lshlrev_b64 v[132:133], 15, v[80:81]
	v_or_b32_e32 v80, s23, v24
	s_add_i32 s22, s18, 8
	s_add_i32 s24, s18, 12
	s_add_i32 s27, s19, 16
	v_lshlrev_b64 v[114:115], 15, v[114:115]
	v_lshl_add_u64 v[130:131], v[22:23], 0, v[130:131]
	v_lshl_add_u64 v[116:117], v[22:23], 0, v[116:117]
	v_lshlrev_b64 v[134:135], 15, v[80:81]
	v_or_b32_e32 v80, s25, v24
	v_mov_b32_e32 v119, v1
	v_mov_b32_e32 v121, v1
	s_add_i32 s29, s19, 20
	v_or_b32_e32 v118, s22, v5
	v_or_b32_e32 v120, s24, v5
	v_lshl_add_u64 v[114:115], v[22:23], 0, v[114:115]
	v_lshl_add_u64 v[132:133], v[22:23], 0, v[132:133]
	global_load_dword v101, v[130:131], off
	global_load_dword v113, v[114:115], off
	global_load_dword v146, v[132:133], off
	global_load_dword v147, v[116:117], off
	v_lshlrev_b64 v[116:117], 15, v[80:81]
	v_or_b32_e32 v80, s27, v24
	s_add_i32 s26, s18, 16
	s_add_i32 s28, s18, 20
	s_add_i32 s31, s19, 24
	v_lshlrev_b64 v[118:119], 15, v[118:119]
	v_lshlrev_b64 v[120:121], 15, v[120:121]
	v_lshl_add_u64 v[114:115], v[22:23], 0, v[134:135]
	v_lshl_add_u64 v[116:117], v[22:23], 0, v[116:117]
	v_lshlrev_b64 v[130:131], 15, v[80:81]
	v_or_b32_e32 v80, s29, v24
	v_mov_b32_e32 v123, v1
	v_mov_b32_e32 v125, v1
	s_add_i32 s30, s18, 24
	s_add_i32 s33, s18, 28
	s_add_i32 s35, s19, 28
	v_or_b32_e32 v122, s26, v5
	v_or_b32_e32 v124, s28, v5
	v_lshl_add_u64 v[118:119], v[22:23], 0, v[118:119]
	v_lshl_add_u64 v[120:121], v[22:23], 0, v[120:121]
	global_load_dword v148, v[114:115], off
	global_load_dword v149, v[118:119], off
	global_load_dword v150, v[116:117], off
	global_load_dword v151, v[120:121], off
	v_lshlrev_b64 v[116:117], 15, v[80:81]
	v_or_b32_e32 v80, s31, v24
	v_mov_b32_e32 v127, v1
	v_mov_b32_e32 v129, v1
	v_or_b32_e32 v126, s30, v5
	v_or_b32_e32 v128, s33, v5
	v_lshlrev_b64 v[122:123], 15, v[122:123]
	v_lshlrev_b64 v[124:125], 15, v[124:125]
	v_lshl_add_u64 v[114:115], v[22:23], 0, v[130:131]
	v_lshl_add_u64 v[116:117], v[22:23], 0, v[116:117]
	v_lshlrev_b64 v[118:119], 15, v[80:81]
	v_or_b32_e32 v80, s35, v24
	v_lshlrev_b64 v[126:127], 15, v[126:127]
	v_lshlrev_b64 v[128:129], 15, v[128:129]
	v_lshl_add_u64 v[122:123], v[22:23], 0, v[122:123]
	v_lshl_add_u64 v[124:125], v[22:23], 0, v[124:125]
	global_load_dword v152, v[114:115], off
	global_load_dword v153, v[122:123], off
	global_load_dword v154, v[116:117], off
	global_load_dword v155, v[124:125], off
	v_lshl_add_u64 v[114:115], v[22:23], 0, v[118:119]
	v_lshlrev_b64 v[116:117], 15, v[80:81]
	v_lshl_add_u64 v[126:127], v[22:23], 0, v[126:127]
	v_lshl_add_u64 v[128:129], v[22:23], 0, v[128:129]
	v_lshl_add_u64 v[116:117], v[22:23], 0, v[116:117]
	global_load_dword v80, v[114:115], off
	global_load_dword v156, v[126:127], off
	global_load_dword v157, v[116:117], off
	global_load_dword v158, v[128:129], off
	v_or_b32_e32 v116, s18, v3
	v_or_b32_e32 v114, s19, v2
	s_add_i32 s16, s16, 16
	s_add_i32 s13, s13, 16
	s_add_i32 s17, s17, -16
	v_mad_u64_u32 v[114:115], s[18:19], v114, s1, v[6:7]
	v_mad_u64_u32 v[116:117], s[18:19], v116, s1, v[6:7]
	v_or_b32_e32 v115, s20, v3
	v_or_b32_e32 v117, s21, v2
	v_or_b32_e32 v124, s22, v3
	v_or_b32_e32 v122, s23, v2
	v_or_b32_e32 v128, s24, v3
	v_or_b32_e32 v126, s25, v2
	v_or_b32_e32 v132, s26, v3
	v_or_b32_e32 v130, s27, v2
	v_or_b32_e32 v136, s28, v3
	v_or_b32_e32 v134, s29, v2
	v_or_b32_e32 v140, s30, v3
	v_or_b32_e32 v138, s31, v2
	v_or_b32_e32 v144, s33, v3
	v_or_b32_e32 v142, s35, v2
	s_cmp_lg_u32 s17, 0
	v_mad_u64_u32 v[118:119], s[18:19], v117, s1, v[6:7]
	v_mad_u64_u32 v[120:121], s[18:19], v115, s1, v[6:7]
	v_mad_u64_u32 v[122:123], s[18:19], v122, s1, v[6:7]
	v_mad_u64_u32 v[124:125], s[18:19], v124, s1, v[6:7]
	v_mad_u64_u32 v[126:127], s[18:19], v126, s1, v[6:7]
	v_mad_u64_u32 v[128:129], s[18:19], v128, s1, v[6:7]
	v_mad_u64_u32 v[130:131], s[18:19], v130, s1, v[6:7]
	v_mad_u64_u32 v[132:133], s[18:19], v132, s1, v[6:7]
	v_mad_u64_u32 v[134:135], s[18:19], v134, s1, v[6:7]
	v_mad_u64_u32 v[136:137], s[18:19], v136, s1, v[6:7]
	v_mad_u64_u32 v[138:139], s[18:19], v138, s1, v[6:7]
	v_mad_u64_u32 v[140:141], s[18:19], v140, s1, v[6:7]
	v_mad_u64_u32 v[142:143], s[18:19], v142, s1, v[6:7]
	v_mad_u64_u32 v[144:145], s[18:19], v144, s1, v[6:7]
	s_lshl_b32 s18, s13, 1
	s_lshl_b32 s19, s16, 1
	v_or_b32_e32 v0, s19, v24
	s_add_i32 s20, s18, 4
	s_add_i32 s21, s19, 4
	v_mov_b32_e32 v37, v1
	s_add_i32 s23, s19, 8
	v_lshlrev_b64 v[50:51], 15, v[0:1]
	v_or_b32_e32 v36, s20, v5
	v_or_b32_e32 v0, s21, v24
	v_mov_b32_e32 v35, v1
	v_or_b32_e32 v34, s18, v5
	s_add_i32 s25, s19, 12
	v_lshlrev_b64 v[36:37], 15, v[36:37]
	v_lshlrev_b64 v[52:53], 15, v[0:1]
	v_or_b32_e32 v0, s23, v24
	s_add_i32 s22, s18, 8
	s_add_i32 s24, s18, 12
	s_add_i32 s27, s19, 16
	v_lshlrev_b64 v[34:35], 15, v[34:35]
	v_lshl_add_u64 v[50:51], v[22:23], 0, v[50:51]
	v_lshl_add_u64 v[36:37], v[22:23], 0, v[36:37]
	v_lshlrev_b64 v[54:55], 15, v[0:1]
	v_or_b32_e32 v0, s25, v24
	v_mov_b32_e32 v39, v1
	v_mov_b32_e32 v41, v1
	s_add_i32 s29, s19, 20
	v_or_b32_e32 v38, s22, v5
	v_or_b32_e32 v40, s24, v5
	v_lshl_add_u64 v[34:35], v[22:23], 0, v[34:35]
	v_lshl_add_u64 v[52:53], v[22:23], 0, v[52:53]
	global_load_dword v21, v[50:51], off
	global_load_dword v33, v[34:35], off
	global_load_dword v66, v[52:53], off
;     ...
; #pragma unroll 8
;     for (int i = 0; i < 32; ++i) { const int kk = 2 * i + (lane >> 5); scr[kk * 33 + (lane & 31)] = W[(size_t)(k0 + kk) * N + n0 + (lane & 31)]; }
	global_load_dword v67, v[36:37], off
	v_lshlrev_b64 v[36:37], 15, v[0:1]
	v_or_b32_e32 v0, s27, v24
	s_add_i32 s26, s18, 16
	s_add_i32 s28, s18, 20
	s_add_i32 s31, s19, 24
	v_lshlrev_b64 v[38:39], 15, v[38:39]
	v_lshlrev_b64 v[40:41], 15, v[40:41]
	v_lshl_add_u64 v[34:35], v[22:23], 0, v[54:55]
	v_lshl_add_u64 v[36:37], v[22:23], 0, v[36:37]
	v_lshlrev_b64 v[50:51], 15, v[0:1]
	v_or_b32_e32 v0, s29, v24
	v_mov_b32_e32 v43, v1
	v_mov_b32_e32 v45, v1
	s_add_i32 s30, s18, 24
	s_add_i32 s33, s18, 28
	s_add_i32 s35, s19, 28
	v_or_b32_e32 v42, s26, v5
	v_or_b32_e32 v44, s28, v5
	v_lshl_add_u64 v[38:39], v[22:23], 0, v[38:39]
	v_lshl_add_u64 v[40:41], v[22:23], 0, v[40:41]
	global_load_dword v68, v[34:35], off
	global_load_dword v69, v[38:39], off
	global_load_dword v70, v[36:37], off
	global_load_dword v71, v[40:41], off
	v_lshlrev_b64 v[36:37], 15, v[0:1]
	v_or_b32_e32 v0, s31, v24
	v_mov_b32_e32 v47, v1
	v_mov_b32_e32 v49, v1
	v_or_b32_e32 v46, s30, v5
	v_or_b32_e32 v48, s33, v5
	v_lshlrev_b64 v[42:43], 15, v[42:43]
	v_lshlrev_b64 v[44:45], 15, v[44:45]
	v_lshl_add_u64 v[34:35], v[22:23], 0, v[50:51]
	v_lshl_add_u64 v[36:37], v[22:23], 0, v[36:37]
	v_lshlrev_b64 v[38:39], 15, v[0:1]
	v_or_b32_e32 v0, s35, v24
	v_lshlrev_b64 v[46:47], 15, v[46:47]
	v_lshlrev_b64 v[48:49], 15, v[48:49]
	v_lshl_add_u64 v[42:43], v[22:23], 0, v[42:43]
	v_lshl_add_u64 v[44:45], v[22:23], 0, v[44:45]
	global_load_dword v72, v[34:35], off
	global_load_dword v73, v[42:43], off
	global_load_dword v74, v[36:37], off
	global_load_dword v75, v[44:45], off
	v_lshl_add_u64 v[34:35], v[22:23], 0, v[38:39]
	v_lshlrev_b64 v[36:37], 15, v[0:1]
	v_lshl_add_u64 v[46:47], v[22:23], 0, v[46:47]
	v_lshl_add_u64 v[48:49], v[22:23], 0, v[48:49]
	v_lshl_add_u64 v[36:37], v[22:23], 0, v[36:37]
	global_load_dword v0, v[34:35], off
	global_load_dword v76, v[46:47], off
	global_load_dword v77, v[36:37], off
	global_load_dword v78, v[48:49], off
	v_or_b32_e32 v36, s18, v3
	v_or_b32_e32 v34, s19, v2
	s_add_i32 s16, s16, 16
	s_add_i32 s13, s13, 16
	s_add_i32 s17, s17, -16
	v_mad_u64_u32 v[34:35], s[18:19], v34, s1, v[6:7]
	v_mad_u64_u32 v[36:37], s[18:19], v36, s1, v[6:7]
	v_or_b32_e32 v35, s20, v3
	v_or_b32_e32 v37, s21, v2
	v_or_b32_e32 v44, s22, v3
	v_or_b32_e32 v42, s23, v2
	v_or_b32_e32 v48, s24, v3
	v_or_b32_e32 v46, s25, v2
	v_or_b32_e32 v52, s26, v3
	v_or_b32_e32 v50, s27, v2
	v_or_b32_e32 v56, s28, v3
	v_or_b32_e32 v54, s29, v2
	v_or_b32_e32 v60, s30, v3
	v_or_b32_e32 v58, s31, v2
	v_or_b32_e32 v64, s33, v3
	v_or_b32_e32 v62, s35, v2
	s_cmp_lg_u32 s17, 0
	v_mad_u64_u32 v[38:39], s[18:19], v37, s1, v[6:7]
	v_mad_u64_u32 v[40:41], s[18:19], v35, s1, v[6:7]
	v_mad_u64_u32 v[42:43], s[18:19], v42, s1, v[6:7]
	v_mad_u64_u32 v[44:45], s[18:19], v44, s1, v[6:7]
	v_mad_u64_u32 v[46:47], s[18:19], v46, s1, v[6:7]
	v_mad_u64_u32 v[48:49], s[18:19], v48, s1, v[6:7]
	v_mad_u64_u32 v[50:51], s[18:19], v50, s1, v[6:7]
	v_mad_u64_u32 v[52:53], s[18:19], v52, s1, v[6:7]
	v_mad_u64_u32 v[54:55], s[18:19], v54, s1, v[6:7]
	v_mad_u64_u32 v[56:57], s[18:19], v56, s1, v[6:7]
	v_mad_u64_u32 v[58:59], s[18:19], v58, s1, v[6:7]
	v_mad_u64_u32 v[60:61], s[18:19], v60, s1, v[6:7]
	v_mad_u64_u32 v[62:63], s[18:19], v62, s1, v[6:7]
	v_mad_u64_u32 v[64:65], s[18:19], v64, s1, v[6:7]
	s_waitcnt vmcnt(31)
	ds_write_b32 v114, v101
	s_waitcnt vmcnt(30)
	ds_write_b32 v116, v113
	s_waitcnt vmcnt(29)
	ds_write_b32 v118, v146
	s_waitcnt vmcnt(28)
	ds_write_b32 v120, v147
	s_waitcnt vmcnt(27)
	ds_write_b32 v122, v148
	s_waitcnt vmcnt(26)
	ds_write_b32 v124, v149
	s_waitcnt vmcnt(25)
	ds_write_b32 v126, v150
	s_waitcnt vmcnt(24)
	ds_write_b32 v128, v151
	s_waitcnt vmcnt(23)
	ds_write_b32 v130, v152
	s_waitcnt vmcnt(22)
	ds_write_b32 v132, v153
	s_waitcnt vmcnt(21)
	ds_write_b32 v134, v154
	s_waitcnt vmcnt(20)
	ds_write_b32 v136, v155
	s_waitcnt vmcnt(19)
	ds_write_b32 v138, v80
	s_waitcnt vmcnt(18)
	ds_write_b32 v140, v156
	s_waitcnt vmcnt(17)
	ds_write_b32 v142, v157
	s_waitcnt vmcnt(16)
	ds_write_b32 v144, v158
	s_waitcnt vmcnt(15)
	ds_write_b32 v34, v21
	s_waitcnt vmcnt(14)
	ds_write_b32 v36, v33
	s_waitcnt vmcnt(13)
	ds_write_b32 v38, v66
	s_waitcnt vmcnt(12)
	ds_write_b32 v40, v67
	s_waitcnt vmcnt(11)
	ds_write_b32 v42, v68
	s_waitcnt vmcnt(10)
	ds_write_b32 v44, v69
	s_waitcnt vmcnt(9)
	ds_write_b32 v46, v70
	s_waitcnt vmcnt(8)
	ds_write_b32 v48, v71
	s_waitcnt vmcnt(7)
	ds_write_b32 v50, v72
	s_waitcnt vmcnt(6)
	ds_write_b32 v52, v73
	s_waitcnt vmcnt(5)
	ds_write_b32 v54, v74
	s_waitcnt vmcnt(4)
	ds_write_b32 v56, v75
	s_waitcnt vmcnt(3)
	ds_write_b32 v58, v0
	s_waitcnt vmcnt(2)
	ds_write_b32 v60, v76
	s_waitcnt vmcnt(1)
	ds_write_b32 v62, v77
	s_waitcnt vmcnt(0)
	ds_write_b32 v64, v78
	s_waitcnt lgkmcnt(0)
; #define GAS __attribute__((address_space(1)))
; #define LAS __attribute__((address_space(3)))
; #define LDS_WAIT() asm volatile("s_waitcnt lgkmcnt(0)" ::: "memory")
; __device__ __forceinline__ unsigned pk2(float lo, float hi) { return f2bf(lo) | (f2bf(hi) << 16); }
;     ...
;     const int c = lane & 7;
; #pragma unroll
;     for (int j = 0; j < 4; ++j) { const int n = (lane >> 3) + 8 * j; const LAS float* s = scr + (8 * c) * 33 + n;
;         v4u o; o.x = pk2(s[0 * 33], s[1 * 33]); o.y = pk2(s[2 * 33], s[3 * 33]); o.z = pk2(s[4 * 33], s[5 * 33]); o.w = pk2(s[6 * 33], s[7 * 33]);
;         const int nr = pg ? (8 * ((n >> 2) & 3) + 4 * (n >> 4) + (n & 3)) : n;
;         *(GAS v4u*)(WT + (size_t)(n0 + nr) * K + k0 + 8 * c) = o; }
;     LDS_WAIT(); asm volatile("" ::: "memory");
	ds_read2_b32 v[22:23], v25 offset1:8
	ds_read2_b32 v[40:41], v25 offset0:33 offset1:41
	ds_read2_b32 v[42:43], v25 offset0:66 offset1:74
	ds_read2_b32 v[44:45], v25 offset0:99 offset1:107
	ds_read2_b32 v[46:47], v25 offset0:132 offset1:140
	s_waitcnt lgkmcnt(4)
	v_bfe_u32 v0, v22, 16, 1
	v_add3_u32 v0, v22, v0, s85
	s_waitcnt lgkmcnt(3)
	v_bfe_u32 v5, v40, 16, 1
	v_lshrrev_b32_e32 v0, 16, v0
	v_add3_u32 v5, v40, v5, s85
	ds_read2_b32 v[48:49], v25 offset0:165 offset1:173
	v_and_or_b32 v34, v5, s3, v0
	s_waitcnt lgkmcnt(3)
	v_bfe_u32 v0, v42, 16, 1
	v_add3_u32 v0, v42, v0, s85
	s_waitcnt lgkmcnt(2)
	v_bfe_u32 v5, v44, 16, 1
	ds_read2_b32 v[50:51], v25 offset0:198 offset1:206
	v_lshrrev_b32_e32 v0, 16, v0
	v_add3_u32 v5, v44, v5, s85
	ds_read2_b32 v[52:53], v25 offset0:231 offset1:239
	v_and_or_b32 v35, v5, s3, v0
	s_waitcnt lgkmcnt(3)
	v_bfe_u32 v0, v46, 16, 1
	v_add3_u32 v0, v46, v0, s85
	s_waitcnt lgkmcnt(2)
	v_bfe_u32 v5, v48, 16, 1
	v_lshrrev_b32_e32 v0, 16, v0
	v_add3_u32 v5, v48, v5, s85
	v_and_or_b32 v36, v5, s3, v0
	s_waitcnt lgkmcnt(1)
	v_bfe_u32 v0, v50, 16, 1
	s_cmpk_lt_u32 s12, 0x80
	v_add3_u32 v0, v50, v0, s85
	s_waitcnt lgkmcnt(0)
	v_bfe_u32 v5, v52, 16, 1
	s_cselect_b64 vcc, -1, 0
	v_lshrrev_b32_e32 v0, 16, v0
	v_add3_u32 v5, v52, v5, s85
	v_and_or_b32 v37, v5, s3, v0
	v_cndmask_b32_e32 v0, v7, v29, vcc
	s_lshl_b32 s78, s11, 1
	v_or_b32_e32 v0, s10, v0
	v_lshl_add_u64 v[38:39], v[16:17], 0, s[78:79]
	v_lshlrev_b32_e32 v0, 12, v0
	v_lshl_add_u64 v[54:55], v[38:39], 0, v[0:1]
	v_bfe_u32 v0, v23, 16, 1
	v_add3_u32 v0, v23, v0, s85
	v_bfe_u32 v5, v41, 16, 1
	v_lshrrev_b32_e32 v0, 16, v0
	v_add3_u32 v5, v41, v5, s85
	global_store_dwordx4 v[54:55], v[34:37], off
	ds_read2_b32 v[22:23], v25 offset0:16 offset1:24
	s_nop 0
	v_and_or_b32 v34, v5, s3, v0
	v_bfe_u32 v0, v43, 16, 1
	v_add3_u32 v0, v43, v0, s85
	v_bfe_u32 v5, v45, 16, 1
	v_lshrrev_b32_e32 v0, 16, v0
	v_add3_u32 v5, v45, v5, s85
	v_and_or_b32 v35, v5, s3, v0
	v_bfe_u32 v0, v47, 16, 1
	v_add3_u32 v0, v47, v0, s85
	v_bfe_u32 v5, v49, 16, 1
	v_lshrrev_b32_e32 v0, 16, v0
	v_add3_u32 v5, v49, v5, s85
	v_and_or_b32 v36, v5, s3, v0
	v_bfe_u32 v0, v51, 16, 1
	v_add3_u32 v0, v51, v0, s85
	v_bfe_u32 v5, v53, 16, 1
	v_lshrrev_b32_e32 v0, 16, v0
	v_add3_u32 v5, v53, v5, s85
	v_and_or_b32 v37, v5, s3, v0
	v_cndmask_b32_e32 v0, v26, v30, vcc
	v_or_b32_e32 v0, s10, v0
	v_lshlrev_b32_e32 v0, 12, v0
	v_lshl_add_u64 v[40:41], v[38:39], 0, v[0:1]
	global_store_dwordx4 v[40:41], v[34:37], off
	ds_read2_b32 v[40:41], v25 offset0:49 offset1:57
	ds_read2_b32 v[42:43], v25 offset0:82 offset1:90
	ds_read2_b32 v[44:45], v25 offset0:115 offset1:123
	s_waitcnt lgkmcnt(3)
	v_bfe_u32 v0, v22, 16, 1
	v_add3_u32 v0, v22, v0, s85
	s_waitcnt lgkmcnt(2)
	v_bfe_u32 v5, v40, 16, 1
	ds_read2_b32 v[46:47], v25 offset0:148 offset1:156
	v_lshrrev_b32_e32 v0, 16, v0
	v_add3_u32 v5, v40, v5, s85
	ds_read2_b32 v[48:49], v25 offset0:181 offset1:189
	v_and_or_b32 v34, v5, s3, v0
	s_waitcnt lgkmcnt(3)
	v_bfe_u32 v0, v42, 16, 1
	v_add3_u32 v0, v42, v0, s85
	s_waitcnt lgkmcnt(2)
	v_bfe_u32 v5, v44, 16, 1
	ds_read2_b32 v[50:51], v25 offset0:214 offset1:222
	v_lshrrev_b32_e32 v0, 16, v0
	v_add3_u32 v5, v44, v5, s85
	ds_read2_b32 v[52:53], v25 offset0:247 offset1:255
	v_and_or_b32 v35, v5, s3, v0
	s_waitcnt lgkmcnt(3)
	v_bfe_u32 v0, v46, 16, 1
	v_add3_u32 v0, v46, v0, s85
	s_waitcnt lgkmcnt(2)
	v_bfe_u32 v5, v48, 16, 1
	v_lshrrev_b32_e32 v0, 16, v0
	v_add3_u32 v5, v48, v5, s85
	v_and_or_b32 v36, v5, s3, v0
	s_waitcnt lgkmcnt(1)
	v_bfe_u32 v0, v50, 16, 1
	v_add3_u32 v0, v50, v0, s85
	s_waitcnt lgkmcnt(0)
	v_bfe_u32 v5, v52, 16, 1
	v_lshrrev_b32_e32 v0, 16, v0
	v_add3_u32 v5, v52, v5, s85
	v_and_or_b32 v37, v5, s3, v0
	v_cndmask_b32_e32 v0, v27, v31, vcc
	v_or_b32_e32 v0, s10, v0
	v_lshlrev_b32_e32 v0, 12, v0
	v_lshl_add_u64 v[54:55], v[38:39], 0, v[0:1]
	v_bfe_u32 v0, v23, 16, 1
	v_add3_u32 v0, v23, v0, s85
	v_bfe_u32 v5, v41, 16, 1
	v_lshrrev_b32_e32 v0, 16, v0
	v_add3_u32 v5, v41, v5, s85
	global_store_dwordx4 v[54:55], v[34:37], off
	s_nop 1
	v_and_or_b32 v34, v5, s3, v0
	v_bfe_u32 v0, v43, 16, 1
	v_add3_u32 v0, v43, v0, s85
	v_bfe_u32 v5, v45, 16, 1
	v_lshrrev_b32_e32 v0, 16, v0
	v_add3_u32 v5, v45, v5, s85
	v_and_or_b32 v35, v5, s3, v0
	v_bfe_u32 v0, v47, 16, 1
	v_add3_u32 v0, v47, v0, s85
	v_bfe_u32 v5, v49, 16, 1
	v_lshrrev_b32_e32 v0, 16, v0
	v_add3_u32 v5, v49, v5, s85
	v_and_or_b32 v36, v5, s3, v0
	v_bfe_u32 v0, v51, 16, 1
	v_add3_u32 v0, v51, v0, s85
	v_bfe_u32 v5, v53, 16, 1
	v_lshrrev_b32_e32 v0, 16, v0
	v_add3_u32 v5, v53, v5, s85
	v_and_or_b32 v37, v5, s3, v0
	v_cndmask_b32_e32 v0, v28, v32, vcc
	v_or_b32_e32 v0, s10, v0
	v_lshlrev_b32_e32 v0, 12, v0
	v_lshl_add_u64 v[22:23], v[38:39], 0, v[0:1]
	global_store_dwordx4 v[22:23], v[34:37], off
	s_waitcnt lgkmcnt(0)

;     ...
; #pragma unroll 8
;     for (int i = 0; i < 32; ++i) { const int kk = 2 * i + (lane >> 5); scr[kk * 33 + (lane & 31)] = W[(size_t)(k0 + kk) * N + n0 + (lane & 31)]; }
.LBB0_440:
	s_lshl_b32 s18, s11, 1
	s_lshl_b32 s19, s16, 1
	v_or_b32_e32 v116, s19, v0
	s_add_i32 s20, s18, 4
	s_add_i32 s21, s19, 4
	s_add_i32 s22, s18, 8
	s_add_i32 s23, s19, 8
	s_add_i32 s24, s18, 12
	s_add_i32 s25, s19, 12
	s_add_i32 s26, s18, 16
	s_add_i32 s27, s19, 16
	s_add_i32 s28, s18, 20
	s_add_i32 s29, s19, 20
	s_add_i32 s30, s18, 24
	s_add_i32 s31, s19, 24
	s_add_i32 s33, s18, 28
	s_add_i32 s35, s19, 28
	v_or_b32_e32 v114, s18, v5
	v_ashrrev_i32_e32 v117, 31, v116
	v_or_b32_e32 v118, s20, v5
	v_or_b32_e32 v120, s21, v0
	v_or_b32_e32 v122, s22, v5
	v_or_b32_e32 v124, s23, v0
	v_or_b32_e32 v126, s24, v5
	v_or_b32_e32 v128, s25, v0
	v_or_b32_e32 v130, s26, v5
	v_or_b32_e32 v132, s27, v0
	v_or_b32_e32 v134, s28, v5
	v_or_b32_e32 v136, s29, v0
	v_or_b32_e32 v138, s30, v5
	v_or_b32_e32 v140, s31, v0
	v_or_b32_e32 v142, s33, v5
	v_or_b32_e32 v144, s35, v0
	v_ashrrev_i32_e32 v115, 31, v114
	v_lshlrev_b64 v[116:117], 15, v[116:117]
	v_ashrrev_i32_e32 v121, 31, v120
	v_ashrrev_i32_e32 v119, 31, v118
	v_ashrrev_i32_e32 v125, 31, v124
	v_ashrrev_i32_e32 v123, 31, v122
	v_ashrrev_i32_e32 v129, 31, v128
	v_ashrrev_i32_e32 v127, 31, v126
	v_ashrrev_i32_e32 v133, 31, v132
	v_ashrrev_i32_e32 v131, 31, v130
	v_ashrrev_i32_e32 v137, 31, v136
	v_ashrrev_i32_e32 v135, 31, v134
	v_ashrrev_i32_e32 v141, 31, v140
	v_ashrrev_i32_e32 v139, 31, v138
	v_ashrrev_i32_e32 v145, 31, v144
	v_ashrrev_i32_e32 v143, 31, v142
	v_lshlrev_b64 v[114:115], 15, v[114:115]
	v_lshl_add_u64 v[116:117], v[22:23], 0, v[116:117]
	v_lshlrev_b64 v[118:119], 15, v[118:119]
	v_lshlrev_b64 v[120:121], 15, v[120:121]
	v_lshlrev_b64 v[122:123], 15, v[122:123]
	v_lshlrev_b64 v[124:125], 15, v[124:125]
	v_lshlrev_b64 v[126:127], 15, v[126:127]
	v_lshlrev_b64 v[128:129], 15, v[128:129]
	v_lshlrev_b64 v[130:131], 15, v[130:131]
	v_lshlrev_b64 v[132:133], 15, v[132:133]
	v_lshlrev_b64 v[134:135], 15, v[134:135]
	v_lshlrev_b64 v[136:137], 15, v[136:137]
	v_lshlrev_b64 v[138:139], 15, v[138:139]
	v_lshlrev_b64 v[140:141], 15, v[140:141]
	v_lshlrev_b64 v[142:143], 15, v[142:143]
	v_lshlrev_b64 v[144:145], 15, v[144:145]
	v_lshl_add_u64 v[114:115], v[22:23], 0, v[114:115]
	v_lshl_add_u64 v[120:121], v[22:23], 0, v[120:121]
	v_lshl_add_u64 v[118:119], v[22:23], 0, v[118:119]
	v_lshl_add_u64 v[124:125], v[22:23], 0, v[124:125]
	v_lshl_add_u64 v[122:123], v[22:23], 0, v[122:123]
	v_lshl_add_u64 v[128:129], v[22:23], 0, v[128:129]
	v_lshl_add_u64 v[126:127], v[22:23], 0, v[126:127]
	v_lshl_add_u64 v[132:133], v[22:23], 0, v[132:133]
	v_lshl_add_u64 v[130:131], v[22:23], 0, v[130:131]
	v_lshl_add_u64 v[136:137], v[22:23], 0, v[136:137]
	v_lshl_add_u64 v[134:135], v[22:23], 0, v[134:135]
	v_lshl_add_u64 v[140:141], v[22:23], 0, v[140:141]
	v_lshl_add_u64 v[138:139], v[22:23], 0, v[138:139]
	v_lshl_add_u64 v[144:145], v[22:23], 0, v[144:145]
	v_lshl_add_u64 v[142:143], v[22:23], 0, v[142:143]
	global_load_dword v101, v[116:117], off
	global_load_dword v104, v[114:115], off
	global_load_dword v113, v[120:121], off
	global_load_dword v146, v[118:119], off
	global_load_dword v147, v[124:125], off
	global_load_dword v148, v[122:123], off
	global_load_dword v149, v[128:129], off
	global_load_dword v150, v[126:127], off
	global_load_dword v151, v[132:133], off
	global_load_dword v152, v[130:131], off
	global_load_dword v153, v[136:137], off
	global_load_dword v154, v[134:135], off
	global_load_dword v155, v[140:141], off
	global_load_dword v156, v[138:139], off
	global_load_dword v157, v[144:145], off
	global_load_dword v158, v[142:143], off
	v_or_b32_e32 v116, s18, v3
	v_or_b32_e32 v114, s19, v2
	s_add_i32 s16, s16, 16
	s_add_i32 s11, s11, 16
	s_add_i32 s17, s17, -16
	v_mad_u64_u32 v[114:115], s[18:19], v114, s1, v[6:7]
	v_mad_u64_u32 v[116:117], s[18:19], v116, s1, v[6:7]
	v_or_b32_e32 v115, s20, v3
	v_or_b32_e32 v117, s21, v2
	v_or_b32_e32 v124, s22, v3
	v_or_b32_e32 v122, s23, v2
	v_or_b32_e32 v128, s24, v3
	v_or_b32_e32 v126, s25, v2
	v_or_b32_e32 v132, s26, v3
	v_or_b32_e32 v130, s27, v2
	v_or_b32_e32 v136, s28, v3
	v_or_b32_e32 v134, s29, v2
	v_or_b32_e32 v140, s30, v3
	v_or_b32_e32 v138, s31, v2
	v_or_b32_e32 v144, s33, v3
	v_or_b32_e32 v142, s35, v2
	s_cmp_lg_u32 s17, 0
	v_mad_u64_u32 v[118:119], s[18:19], v117, s1, v[6:7]
	v_mad_u64_u32 v[120:121], s[18:19], v115, s1, v[6:7]
	v_mad_u64_u32 v[122:123], s[18:19], v122, s1, v[6:7]
	v_mad_u64_u32 v[124:125], s[18:19], v124, s1, v[6:7]
	v_mad_u64_u32 v[126:127], s[18:19], v126, s1, v[6:7]
	v_mad_u64_u32 v[128:129], s[18:19], v128, s1, v[6:7]
	v_mad_u64_u32 v[130:131], s[18:19], v130, s1, v[6:7]
	v_mad_u64_u32 v[132:133], s[18:19], v132, s1, v[6:7]
	v_mad_u64_u32 v[134:135], s[18:19], v134, s1, v[6:7]
	v_mad_u64_u32 v[136:137], s[18:19], v136, s1, v[6:7]
	v_mad_u64_u32 v[138:139], s[18:19], v138, s1, v[6:7]
	v_mad_u64_u32 v[140:141], s[18:19], v140, s1, v[6:7]
	v_mad_u64_u32 v[142:143], s[18:19], v142, s1, v[6:7]
	v_mad_u64_u32 v[144:145], s[18:19], v144, s1, v[6:7]
	s_lshl_b32 s18, s11, 1
	s_lshl_b32 s19, s16, 1
	v_or_b32_e32 v36, s19, v0
	s_add_i32 s20, s18, 4
	s_add_i32 s21, s19, 4
	s_add_i32 s22, s18, 8
	s_add_i32 s23, s19, 8
	s_add_i32 s24, s18, 12
	s_add_i32 s25, s19, 12
	s_add_i32 s26, s18, 16
	s_add_i32 s27, s19, 16
	s_add_i32 s28, s18, 20
	s_add_i32 s29, s19, 20
	s_add_i32 s30, s18, 24
	s_add_i32 s31, s19, 24
	s_add_i32 s33, s18, 28
	s_add_i32 s35, s19, 28
	v_or_b32_e32 v34, s18, v5
	v_ashrrev_i32_e32 v37, 31, v36
	v_or_b32_e32 v38, s20, v5
	v_or_b32_e32 v40, s21, v0
	v_or_b32_e32 v42, s22, v5
	v_or_b32_e32 v44, s23, v0
	v_or_b32_e32 v46, s24, v5
	v_or_b32_e32 v48, s25, v0
	v_or_b32_e32 v50, s26, v5
	v_or_b32_e32 v52, s27, v0
;     ...
; #pragma unroll 8
;     for (int i = 0; i < 32; ++i) { const int kk = 2 * i + (lane >> 5); scr[kk * 33 + (lane & 31)] = W[(size_t)(k0 + kk) * N + n0 + (lane & 31)]; }
	v_or_b32_e32 v54, s28, v5
	v_or_b32_e32 v56, s29, v0
	v_or_b32_e32 v58, s30, v5
	v_or_b32_e32 v60, s31, v0
	v_or_b32_e32 v62, s33, v5
	v_or_b32_e32 v64, s35, v0
	v_ashrrev_i32_e32 v35, 31, v34
	v_lshlrev_b64 v[36:37], 15, v[36:37]
	v_ashrrev_i32_e32 v41, 31, v40
	v_ashrrev_i32_e32 v39, 31, v38
	v_ashrrev_i32_e32 v45, 31, v44
	v_ashrrev_i32_e32 v43, 31, v42
	v_ashrrev_i32_e32 v49, 31, v48
	v_ashrrev_i32_e32 v47, 31, v46
	v_ashrrev_i32_e32 v53, 31, v52
	v_ashrrev_i32_e32 v51, 31, v50
	v_ashrrev_i32_e32 v57, 31, v56
	v_ashrrev_i32_e32 v55, 31, v54
	v_ashrrev_i32_e32 v61, 31, v60
	v_ashrrev_i32_e32 v59, 31, v58
	v_ashrrev_i32_e32 v65, 31, v64
	v_ashrrev_i32_e32 v63, 31, v62
	v_lshlrev_b64 v[34:35], 15, v[34:35]
	v_lshl_add_u64 v[36:37], v[22:23], 0, v[36:37]
	v_lshlrev_b64 v[38:39], 15, v[38:39]
	v_lshlrev_b64 v[40:41], 15, v[40:41]
	v_lshlrev_b64 v[42:43], 15, v[42:43]
	v_lshlrev_b64 v[44:45], 15, v[44:45]
	v_lshlrev_b64 v[46:47], 15, v[46:47]
	v_lshlrev_b64 v[48:49], 15, v[48:49]
	v_lshlrev_b64 v[50:51], 15, v[50:51]
	v_lshlrev_b64 v[52:53], 15, v[52:53]
	v_lshlrev_b64 v[54:55], 15, v[54:55]
	v_lshlrev_b64 v[56:57], 15, v[56:57]
	v_lshlrev_b64 v[58:59], 15, v[58:59]
	v_lshlrev_b64 v[60:61], 15, v[60:61]
	v_lshlrev_b64 v[62:63], 15, v[62:63]
	v_lshlrev_b64 v[64:65], 15, v[64:65]
	v_lshl_add_u64 v[34:35], v[22:23], 0, v[34:35]
	v_lshl_add_u64 v[40:41], v[22:23], 0, v[40:41]
	v_lshl_add_u64 v[38:39], v[22:23], 0, v[38:39]
	v_lshl_add_u64 v[44:45], v[22:23], 0, v[44:45]
	v_lshl_add_u64 v[42:43], v[22:23], 0, v[42:43]
	v_lshl_add_u64 v[48:49], v[22:23], 0, v[48:49]
	v_lshl_add_u64 v[46:47], v[22:23], 0, v[46:47]
	v_lshl_add_u64 v[52:53], v[22:23], 0, v[52:53]
	v_lshl_add_u64 v[50:51], v[22:23], 0, v[50:51]
	v_lshl_add_u64 v[56:57], v[22:23], 0, v[56:57]
	v_lshl_add_u64 v[54:55], v[22:23], 0, v[54:55]
	v_lshl_add_u64 v[60:61], v[22:23], 0, v[60:61]
	v_lshl_add_u64 v[58:59], v[22:23], 0, v[58:59]
	v_lshl_add_u64 v[64:65], v[22:23], 0, v[64:65]
	v_lshl_add_u64 v[62:63], v[22:23], 0, v[62:63]
	global_load_dword v21, v[36:37], off
	global_load_dword v24, v[34:35], off
	global_load_dword v33, v[40:41], off
	global_load_dword v66, v[38:39], off
	global_load_dword v67, v[44:45], off
	global_load_dword v68, v[42:43], off
	global_load_dword v69, v[48:49], off
	global_load_dword v70, v[46:47], off
	global_load_dword v71, v[52:53], off
	global_load_dword v72, v[50:51], off
	global_load_dword v73, v[56:57], off
	global_load_dword v74, v[54:55], off
	global_load_dword v75, v[60:61], off
	global_load_dword v76, v[58:59], off
	global_load_dword v77, v[64:65], off
	global_load_dword v78, v[62:63], off
	v_or_b32_e32 v36, s18, v3
	v_or_b32_e32 v34, s19, v2
	s_add_i32 s16, s16, 16
	s_add_i32 s11, s11, 16
	s_add_i32 s17, s17, -16
	v_mad_u64_u32 v[34:35], s[18:19], v34, s1, v[6:7]
	v_mad_u64_u32 v[36:37], s[18:19], v36, s1, v[6:7]
	v_or_b32_e32 v35, s20, v3
	v_or_b32_e32 v37, s21, v2
	v_or_b32_e32 v44, s22, v3
	v_or_b32_e32 v42, s23, v2
	v_or_b32_e32 v48, s24, v3
	v_or_b32_e32 v46, s25, v2
	v_or_b32_e32 v52, s26, v3
	v_or_b32_e32 v50, s27, v2
	v_or_b32_e32 v56, s28, v3
	v_or_b32_e32 v54, s29, v2
	v_or_b32_e32 v60, s30, v3
	v_or_b32_e32 v58, s31, v2
	v_or_b32_e32 v64, s33, v3
	v_or_b32_e32 v62, s35, v2
	s_cmp_lg_u32 s17, 0
	v_mad_u64_u32 v[38:39], s[18:19], v37, s1, v[6:7]
	v_mad_u64_u32 v[40:41], s[18:19], v35, s1, v[6:7]
	v_mad_u64_u32 v[42:43], s[18:19], v42, s1, v[6:7]
	v_mad_u64_u32 v[44:45], s[18:19], v44, s1, v[6:7]
	v_mad_u64_u32 v[46:47], s[18:19], v46, s1, v[6:7]
	v_mad_u64_u32 v[48:49], s[18:19], v48, s1, v[6:7]
	v_mad_u64_u32 v[50:51], s[18:19], v50, s1, v[6:7]
	v_mad_u64_u32 v[52:53], s[18:19], v52, s1, v[6:7]
	v_mad_u64_u32 v[54:55], s[18:19], v54, s1, v[6:7]
	v_mad_u64_u32 v[56:57], s[18:19], v56, s1, v[6:7]
	v_mad_u64_u32 v[58:59], s[18:19], v58, s1, v[6:7]
	v_mad_u64_u32 v[60:61], s[18:19], v60, s1, v[6:7]
	v_mad_u64_u32 v[62:63], s[18:19], v62, s1, v[6:7]
	v_mad_u64_u32 v[64:65], s[18:19], v64, s1, v[6:7]
	s_waitcnt vmcnt(31)
	ds_write_b32 v114, v101
	s_waitcnt vmcnt(30)
	ds_write_b32 v116, v104
	s_waitcnt vmcnt(29)
	ds_write_b32 v118, v113
	s_waitcnt vmcnt(28)
	ds_write_b32 v120, v146
	s_waitcnt vmcnt(27)
	ds_write_b32 v122, v147
	s_waitcnt vmcnt(26)
	ds_write_b32 v124, v148
	s_waitcnt vmcnt(25)
	ds_write_b32 v126, v149
	s_waitcnt vmcnt(24)
	ds_write_b32 v128, v150
	s_waitcnt vmcnt(23)
	ds_write_b32 v130, v151
	s_waitcnt vmcnt(22)
	ds_write_b32 v132, v152
	s_waitcnt vmcnt(21)
	ds_write_b32 v134, v153
	s_waitcnt vmcnt(20)
	ds_write_b32 v136, v154
	s_waitcnt vmcnt(19)
	ds_write_b32 v138, v155
	s_waitcnt vmcnt(18)
	ds_write_b32 v140, v156
	s_waitcnt vmcnt(17)
	ds_write_b32 v142, v157
	s_waitcnt vmcnt(16)
	ds_write_b32 v144, v158
	s_waitcnt vmcnt(15)
	ds_write_b32 v34, v21
	s_waitcnt vmcnt(14)
	ds_write_b32 v36, v24
	s_waitcnt vmcnt(13)
	ds_write_b32 v38, v33
	s_waitcnt vmcnt(12)
	ds_write_b32 v40, v66
	s_waitcnt vmcnt(11)
	ds_write_b32 v42, v67
	s_waitcnt vmcnt(10)
	ds_write_b32 v44, v68
	s_waitcnt vmcnt(9)
	ds_write_b32 v46, v69
	s_waitcnt vmcnt(8)
	ds_write_b32 v48, v70
	s_waitcnt vmcnt(7)
	ds_write_b32 v50, v71
	s_waitcnt vmcnt(6)
	ds_write_b32 v52, v72
	s_waitcnt vmcnt(5)
	ds_write_b32 v54, v73
	s_waitcnt vmcnt(4)
; #define GAS __attribute__((address_space(1)))
; #define LAS __attribute__((address_space(3)))
; #define LDS_WAIT() asm volatile("s_waitcnt lgkmcnt(0)" ::: "memory")
; __device__ __forceinline__ unsigned pk2(float lo, float hi) { return f2bf(lo) | (f2bf(hi) << 16); }
;     ...
;     for (int i = 0; i < 32; ++i) { const int kk = 2 * i + (lane >> 5); scr[kk * 33 + (lane & 31)] = W[(size_t)(k0 + kk) * N + n0 + (lane & 31)]; }
;     LDS_WAIT(); asm volatile("" ::: "memory");
;     const int c = lane & 7;
; #pragma unroll
;     for (int j = 0; j < 4; ++j) { const int n = (lane >> 3) + 8 * j; const LAS float* s = scr + (8 * c) * 33 + n;
;         v4u o; o.x = pk2(s[0 * 33], s[1 * 33]); o.y = pk2(s[2 * 33], s[3 * 33]); o.z = pk2(s[4 * 33], s[5 * 33]); o.w = pk2(s[6 * 33], s[7 * 33]);
;         const int nr = pg ? (8 * ((n >> 2) & 3) + 4 * (n >> 4) + (n & 3)) : n;
;         *(GAS v4u*)(WT + (size_t)(n0 + nr) * K + k0 + 8 * c) = o; }
;     LDS_WAIT(); asm volatile("" ::: "memory");
	ds_write_b32 v56, v74
	s_waitcnt vmcnt(3)
	ds_write_b32 v58, v75
	s_waitcnt vmcnt(2)
	ds_write_b32 v60, v76
	s_waitcnt vmcnt(1)
	ds_write_b32 v62, v77
	s_waitcnt vmcnt(0)
	ds_write_b32 v64, v78
	s_waitcnt lgkmcnt(0)
	ds_read2_b32 v[22:23], v25 offset1:8
	ds_read2_b32 v[40:41], v25 offset0:33 offset1:41
	ds_read2_b32 v[42:43], v25 offset0:66 offset1:74
	ds_read2_b32 v[44:45], v25 offset0:99 offset1:107
	ds_read2_b32 v[46:47], v25 offset0:132 offset1:140
	s_waitcnt lgkmcnt(4)
	v_bfe_u32 v0, v22, 16, 1
	v_add3_u32 v0, v22, v0, s85
	s_waitcnt lgkmcnt(3)
	v_bfe_u32 v5, v40, 16, 1
	v_lshrrev_b32_e32 v0, 16, v0
	v_add3_u32 v5, v40, v5, s85
	ds_read2_b32 v[48:49], v25 offset0:165 offset1:173
	v_and_or_b32 v34, v5, s3, v0
	s_waitcnt lgkmcnt(3)
	v_bfe_u32 v0, v42, 16, 1
	v_add3_u32 v0, v42, v0, s85
	s_waitcnt lgkmcnt(2)
	v_bfe_u32 v5, v44, 16, 1
	ds_read2_b32 v[50:51], v25 offset0:198 offset1:206
	v_lshrrev_b32_e32 v0, 16, v0
	v_add3_u32 v5, v44, v5, s85
	ds_read2_b32 v[52:53], v25 offset0:231 offset1:239
	v_and_or_b32 v35, v5, s3, v0
	s_waitcnt lgkmcnt(3)
	v_bfe_u32 v0, v46, 16, 1
	v_add3_u32 v0, v46, v0, s85
	s_waitcnt lgkmcnt(2)
	v_bfe_u32 v5, v48, 16, 1
	v_lshrrev_b32_e32 v0, 16, v0
	v_add3_u32 v5, v48, v5, s85
	v_and_or_b32 v36, v5, s3, v0
	s_waitcnt lgkmcnt(1)
	v_bfe_u32 v0, v50, 16, 1
	s_cmpk_lt_i32 s13, 0x80
	v_add3_u32 v0, v50, v0, s85
	s_waitcnt lgkmcnt(0)
	v_bfe_u32 v5, v52, 16, 1
	s_cselect_b64 vcc, -1, 0
	v_lshrrev_b32_e32 v0, 16, v0
	v_add3_u32 v5, v52, v5, s85
	v_and_or_b32 v37, v5, s3, v0
	v_cndmask_b32_e32 v0, v7, v29, vcc
	v_or_b32_e32 v54, s10, v0
	s_ashr_i32 s13, s12, 31
	v_ashrrev_i32_e32 v55, 31, v54
	v_bfe_u32 v0, v23, 16, 1
	v_lshl_add_u64 v[38:39], s[12:13], 1, v[18:19]
	v_lshlrev_b64 v[54:55], 12, v[54:55]
	v_add3_u32 v0, v23, v0, s85
	v_bfe_u32 v5, v41, 16, 1
	v_lshl_add_u64 v[54:55], v[38:39], 0, v[54:55]
	v_lshrrev_b32_e32 v0, 16, v0
	v_add3_u32 v5, v41, v5, s85
	global_store_dwordx4 v[54:55], v[34:37], off
	ds_read2_b32 v[40:41], v25 offset0:16 offset1:24
	s_nop 0
	v_and_or_b32 v34, v5, s3, v0
	v_bfe_u32 v0, v43, 16, 1
	v_add3_u32 v0, v43, v0, s85
	v_bfe_u32 v5, v45, 16, 1
	v_lshrrev_b32_e32 v0, 16, v0
	v_add3_u32 v5, v45, v5, s85
	v_and_or_b32 v35, v5, s3, v0
	v_bfe_u32 v0, v47, 16, 1
	v_add3_u32 v0, v47, v0, s85
	v_bfe_u32 v5, v49, 16, 1
	v_lshrrev_b32_e32 v0, 16, v0
	v_add3_u32 v5, v49, v5, s85
	v_and_or_b32 v36, v5, s3, v0
	v_bfe_u32 v0, v51, 16, 1
	v_add3_u32 v0, v51, v0, s85
	v_bfe_u32 v5, v53, 16, 1
	v_lshrrev_b32_e32 v0, 16, v0
	v_add3_u32 v5, v53, v5, s85
	v_and_or_b32 v37, v5, s3, v0
	v_cndmask_b32_e32 v0, v26, v30, vcc
	v_or_b32_e32 v22, s10, v0
	v_ashrrev_i32_e32 v23, 31, v22
	v_lshlrev_b64 v[22:23], 12, v[22:23]
	v_lshl_add_u64 v[22:23], v[38:39], 0, v[22:23]
	global_store_dwordx4 v[22:23], v[34:37], off
	ds_read2_b32 v[22:23], v25 offset0:49 offset1:57
	ds_read2_b32 v[42:43], v25 offset0:82 offset1:90
	ds_read2_b32 v[44:45], v25 offset0:115 offset1:123
	s_waitcnt lgkmcnt(3)
	v_bfe_u32 v0, v40, 16, 1
	v_add3_u32 v0, v40, v0, s85
	s_waitcnt lgkmcnt(2)
	v_bfe_u32 v5, v22, 16, 1
	ds_read2_b32 v[46:47], v25 offset0:148 offset1:156
	v_lshrrev_b32_e32 v0, 16, v0
	v_add3_u32 v5, v22, v5, s85
	ds_read2_b32 v[48:49], v25 offset0:181 offset1:189
	v_and_or_b32 v34, v5, s3, v0
	s_waitcnt lgkmcnt(3)
	v_bfe_u32 v0, v42, 16, 1
	v_add3_u32 v0, v42, v0, s85
	s_waitcnt lgkmcnt(2)
	v_bfe_u32 v5, v44, 16, 1
	ds_read2_b32 v[50:51], v25 offset0:214 offset1:222
	v_lshrrev_b32_e32 v0, 16, v0
	v_add3_u32 v5, v44, v5, s85
	ds_read2_b32 v[52:53], v25 offset0:247 offset1:255
	v_and_or_b32 v35, v5, s3, v0
	s_waitcnt lgkmcnt(3)
	v_bfe_u32 v0, v46, 16, 1
	v_add3_u32 v0, v46, v0, s85
	s_waitcnt lgkmcnt(2)
	v_bfe_u32 v5, v48, 16, 1
	v_lshrrev_b32_e32 v0, 16, v0
	v_add3_u32 v5, v48, v5, s85
	v_and_or_b32 v36, v5, s3, v0
	s_waitcnt lgkmcnt(1)
	v_bfe_u32 v0, v50, 16, 1
	v_add3_u32 v0, v50, v0, s85
	s_waitcnt lgkmcnt(0)
	v_bfe_u32 v5, v52, 16, 1
	v_lshrrev_b32_e32 v0, 16, v0
	v_add3_u32 v5, v52, v5, s85
	v_and_or_b32 v37, v5, s3, v0
	v_cndmask_b32_e32 v0, v27, v31, vcc
	v_or_b32_e32 v54, s10, v0
	v_ashrrev_i32_e32 v55, 31, v54
	v_bfe_u32 v0, v41, 16, 1
	v_lshlrev_b64 v[54:55], 12, v[54:55]
	v_add3_u32 v0, v41, v0, s85
	v_bfe_u32 v5, v23, 16, 1
	v_lshl_add_u64 v[54:55], v[38:39], 0, v[54:55]
	v_lshrrev_b32_e32 v0, 16, v0
	v_add3_u32 v5, v23, v5, s85
	global_store_dwordx4 v[54:55], v[34:37], off
	s_nop 1
	v_and_or_b32 v34, v5, s3, v0
	v_bfe_u32 v0, v43, 16, 1
	v_add3_u32 v0, v43, v0, s85
	v_bfe_u32 v5, v45, 16, 1
	v_lshrrev_b32_e32 v0, 16, v0
	v_add3_u32 v5, v45, v5, s85
	v_and_or_b32 v35, v5, s3, v0
	v_bfe_u32 v0, v47, 16, 1
	v_add3_u32 v0, v47, v0, s85
	v_bfe_u32 v5, v49, 16, 1
	v_lshrrev_b32_e32 v0, 16, v0
	v_add3_u32 v5, v49, v5, s85
	v_and_or_b32 v36, v5, s3, v0
	v_bfe_u32 v0, v51, 16, 1
	v_add3_u32 v0, v51, v0, s85
	v_bfe_u32 v5, v53, 16, 1
	v_lshrrev_b32_e32 v0, 16, v0
	v_add3_u32 v5, v53, v5, s85
	v_and_or_b32 v37, v5, s3, v0
	v_cndmask_b32_e32 v0, v28, v32, vcc
	v_or_b32_e32 v22, s10, v0
	v_ashrrev_i32_e32 v23, 31, v22
	v_lshlrev_b64 v[22:23], 12, v[22:23]
	v_lshl_add_u64 v[22:23], v[38:39], 0, v[22:23]
	global_store_dwordx4 v[22:23], v[34:37], off
	s_waitcnt lgkmcnt(0)
	s_branch .LBB0_397
